# P0 transposes: per-tile norm gains preloaded with 16 uniform dwordx4 loads instead of 32 serialized load+vmcnt0 pairs
# speedup vs baseline: 1.0019x; 1.0019x over previous
; template <bool F8> __device__ __forceinline__ void transpose_item(const float* W, int K, int N, int ld, void* WTv, const float* kscale, float wscale, LAS float* scr, int item, int lane_) {
;     ...
;     const int nblk = N / 64, kb = item / nblk, nb = item % nblk, k0 = 64 * kb, n0 = 64 * nb;
;     float v[64];
; #pragma unroll
;     for (int kk = 0; kk < 64; ++kk) v[kk] = W[(size_t)(k0 + kk) * ld + n0 + lane];
; #pragma unroll
;     for (int kk = 0; kk < 64; ++kk) { const float sc = (kscale ? kscale[k0 + kk] : 1.f) * wscale; scr[kk * 65 + lane] = v[kk] * sc; }
.LBB0_25:
	s_mul_hi_i32 s0, s15, 0x38e38e39
	s_lshr_b32 s1, s0, 31
	s_ashr_i32 s16, s0, 4
	s_add_i32 s16, s16, s1
	s_mul_i32 s0, s16, 0xffffee00
	s_add_i32 s0, s14, s0
	s_ashr_i32 s1, s0, 31
	s_lshl_b32 s4, s16, 6
	s_lshl_b64 s[0:1], s[0:1], 2
	v_mov_b32_e32 v0, v18
	s_add_u32 s0, s12, s0
	s_addc_u32 s1, s13, s1
	v_ashrrev_i32_e32 v1, 31, v0
	v_lshl_add_u64 v[2:3], v[0:1], 2, s[0:1]
	v_mad_i64_i32 v[4:5], s[0:1], s4, v90, v[2:3]
	s_or_b32 s0, s4, 1
	s_nop 0
	v_mad_i64_i32 v[6:7], s[0:1], s0, v90, v[2:3]
	s_or_b32 s0, s4, 2
	s_nop 0
	v_mad_i64_i32 v[8:9], s[0:1], s0, v90, v[2:3]
	s_or_b32 s0, s4, 3
	s_nop 0
	v_mad_i64_i32 v[10:11], s[0:1], s0, v90, v[2:3]
	s_or_b32 s0, s4, 4
	s_nop 0
	v_mad_i64_i32 v[12:13], s[0:1], s0, v90, v[2:3]
	s_or_b32 s0, s4, 5
	s_nop 0
	v_mad_i64_i32 v[14:15], s[0:1], s0, v90, v[2:3]
	s_or_b32 s0, s4, 6
	s_nop 0
	v_mad_i64_i32 v[24:25], s[0:1], s0, v90, v[2:3]
	s_or_b32 s0, s4, 7
	s_nop 0
	v_mad_i64_i32 v[26:27], s[0:1], s0, v90, v[2:3]
	s_or_b32 s0, s4, 8
	s_cmp_lg_u64 s[6:7], 0
	s_cbranch_scc0 .Lks_skip_lbb0_25
	s_lshl_b32 s20, s4, 2
	s_add_u32 s20, s6, s20
	s_addc_u32 s21, s7, 0
	global_load_dwordx4 v[180:183], v21, s[20:21]
	global_load_dwordx4 v[184:187], v21, s[20:21] offset:16
	global_load_dwordx4 v[188:191], v21, s[20:21] offset:32
	global_load_dwordx4 v[192:195], v21, s[20:21] offset:48
	global_load_dwordx4 v[196:199], v21, s[20:21] offset:64
	global_load_dwordx4 v[200:203], v21, s[20:21] offset:80
	global_load_dwordx4 v[204:207], v21, s[20:21] offset:96
	global_load_dwordx4 v[208:211], v21, s[20:21] offset:112
	global_load_dwordx4 v[212:215], v21, s[20:21] offset:128
	global_load_dwordx4 v[216:219], v21, s[20:21] offset:144
	global_load_dwordx4 v[220:223], v21, s[20:21] offset:160
	global_load_dwordx4 v[224:227], v21, s[20:21] offset:176
	global_load_dwordx4 v[228:231], v21, s[20:21] offset:192
	global_load_dwordx4 v[232:235], v21, s[20:21] offset:208
	global_load_dwordx4 v[236:239], v21, s[20:21] offset:224
	global_load_dwordx4 v[240:243], v21, s[20:21] offset:240
; template <bool F8> __device__ __forceinline__ void transpose_item(const float* W, int K, int N, int ld, void* WTv, const float* kscale, float wscale, LAS float* scr, int item, int lane_) {
;     ...
;     for (int kk = 0; kk < 64; ++kk) v[kk] = W[(size_t)(k0 + kk) * ld + n0 + lane];
; #pragma unroll
;     for (int kk = 0; kk < 64; ++kk) { const float sc = (kscale ? kscale[k0 + kk] : 1.f) * wscale; scr[kk * 65 + lane] = v[kk] * sc; }
.Lks_skip_lbb0_25:
	global_load_dword v72, v[4:5], off
	global_load_dword v69, v[6:7], off
	global_load_dword v70, v[8:9], off
	global_load_dword v67, v[10:11], off
	global_load_dword v68, v[12:13], off
	global_load_dword v65, v[14:15], off
	global_load_dword v66, v[24:25], off
	global_load_dword v63, v[26:27], off
	v_mad_i64_i32 v[4:5], s[0:1], s0, v90, v[2:3]
	s_or_b32 s0, s4, 9
	s_nop 0
	v_mad_i64_i32 v[6:7], s[0:1], s0, v90, v[2:3]
	s_or_b32 s0, s4, 10
	s_nop 0
	v_mad_i64_i32 v[8:9], s[0:1], s0, v90, v[2:3]
	s_or_b32 s0, s4, 11
	s_nop 0
	v_mad_i64_i32 v[10:11], s[0:1], s0, v90, v[2:3]
	s_or_b32 s0, s4, 12
	s_nop 0
	v_mad_i64_i32 v[12:13], s[0:1], s0, v90, v[2:3]
	s_or_b32 s0, s4, 13
	s_nop 0
	v_mad_i64_i32 v[14:15], s[0:1], s0, v90, v[2:3]
	s_or_b32 s0, s4, 14
	s_nop 0
	v_mad_i64_i32 v[24:25], s[0:1], s0, v90, v[2:3]
	s_or_b32 s0, s4, 15
	s_nop 0
	v_mad_i64_i32 v[26:27], s[0:1], s0, v90, v[2:3]
	s_or_b32 s0, s4, 16
	global_load_dword v64, v[4:5], off
	global_load_dword v61, v[6:7], off
	global_load_dword v60, v[8:9], off
	global_load_dword v57, v[10:11], off
	global_load_dword v56, v[12:13], off
	global_load_dword v53, v[14:15], off
	global_load_dword v52, v[24:25], off
	global_load_dword v51, v[26:27], off
	v_mad_i64_i32 v[4:5], s[0:1], s0, v90, v[2:3]
	s_or_b32 s0, s4, 17
	s_nop 0
	v_mad_i64_i32 v[6:7], s[0:1], s0, v90, v[2:3]
	s_or_b32 s0, s4, 19
	s_nop 0
	v_mad_i64_i32 v[8:9], s[0:1], s0, v90, v[2:3]
	s_or_b32 s0, s4, 21
	s_nop 0
	v_mad_i64_i32 v[10:11], s[0:1], s0, v90, v[2:3]
	s_or_b32 s0, s4, 23
	s_nop 0
	v_mad_i64_i32 v[12:13], s[0:1], s0, v90, v[2:3]
	s_or_b32 s0, s4, 25
	s_nop 0
	v_mad_i64_i32 v[14:15], s[0:1], s0, v90, v[2:3]
	s_or_b32 s0, s4, 27
	s_nop 0
	v_mad_i64_i32 v[24:25], s[0:1], s0, v90, v[2:3]
	s_or_b32 s0, s4, 29
	s_nop 0
	v_mad_i64_i32 v[26:27], s[0:1], s0, v90, v[2:3]
	s_or_b32 s0, s4, 31
	s_nop 0
	v_mad_i64_i32 v[28:29], s[0:1], s0, v90, v[2:3]
	s_or_b32 s0, s4, 33
	s_nop 0
	v_mad_i64_i32 v[30:31], s[0:1], s0, v90, v[2:3]
	s_or_b32 s0, s4, 35
	s_nop 0
	v_mad_i64_i32 v[32:33], s[0:1], s0, v90, v[2:3]
	s_or_b32 s0, s4, 37
	s_nop 0
	v_mad_i64_i32 v[34:35], s[0:1], s0, v90, v[2:3]
	s_or_b32 s0, s4, 39
	s_nop 0
	v_mad_i64_i32 v[74:75], s[0:1], s0, v90, v[2:3]
	s_or_b32 s0, s4, 41
	s_nop 0
	v_mad_i64_i32 v[78:79], s[0:1], s0, v90, v[2:3]
	s_or_b32 s0, s4, 43
	s_nop 0
	v_mad_i64_i32 v[80:81], s[0:1], s0, v90, v[2:3]
	s_or_b32 s0, s4, 45
	s_nop 0
	v_mad_i64_i32 v[82:83], s[0:1], s0, v90, v[2:3]
	s_or_b32 s0, s4, 47
	s_nop 0
	v_mad_i64_i32 v[84:85], s[0:1], s0, v90, v[2:3]
	s_or_b32 s0, s4, 49
	s_nop 0
	v_mad_i64_i32 v[86:87], s[0:1], s0, v90, v[2:3]
	s_or_b32 s0, s4, 51
	s_nop 0
	v_mad_i64_i32 v[88:89], s[0:1], s0, v90, v[2:3]
	s_or_b32 s0, s4, 53
	s_nop 0
	v_mad_i64_i32 v[92:93], s[0:1], s0, v90, v[2:3]
	s_or_b32 s0, s4, 55
	s_nop 0
	v_mad_i64_i32 v[94:95], s[0:1], s0, v90, v[2:3]
	s_or_b32 s0, s4, 57
	s_nop 0
	v_mad_i64_i32 v[96:97], s[0:1], s0, v90, v[2:3]
	s_or_b32 s0, s4, 59
	s_nop 0
	v_mad_i64_i32 v[98:99], s[0:1], s0, v90, v[2:3]
	s_or_b32 s0, s4, 61
	s_nop 0
	v_mad_i64_i32 v[100:101], s[0:1], s0, v90, v[2:3]
	s_or_b32 s2, s4, 18
	s_or_b32 s0, s4, 63
	v_mad_i64_i32 v[102:103], s[0:1], s0, v90, v[2:3]
	v_mad_i64_i32 v[36:37], s[0:1], s2, v90, v[2:3]
	s_or_b32 s0, s4, 20
	s_nop 0
	v_mad_i64_i32 v[38:39], s[0:1], s0, v90, v[2:3]
	s_or_b32 s0, s4, 22
	s_nop 0
	v_mad_i64_i32 v[40:41], s[0:1], s0, v90, v[2:3]
	s_or_b32 s0, s4, 24
	global_load_dword v59, v[6:7], off
	global_load_dword v55, v[8:9], off
	global_load_dword v76, v[10:11], off
	global_load_dword v49, v[12:13], off
	global_load_dword v50, v[40:41], off
	global_load_dword v54, v[38:39], off
	global_load_dword v58, v[36:37], off
	global_load_dword v62, v[4:5], off
	v_mad_i64_i32 v[4:5], s[0:1], s0, v90, v[2:3]
	s_or_b32 s0, s4, 26
	s_nop 0
	v_mad_i64_i32 v[6:7], s[0:1], s0, v90, v[2:3]
	s_or_b32 s0, s4, 28
	s_nop 0
	v_mad_i64_i32 v[8:9], s[0:1], s0, v90, v[2:3]
	s_or_b32 s0, s4, 30
	s_nop 0
	v_mad_i64_i32 v[10:11], s[0:1], s0, v90, v[2:3]
	s_or_b32 s0, s4, 32
	global_load_dword v47, v[14:15], off
	global_load_dword v45, v[24:25], off
	global_load_dword v43, v[26:27], off
	global_load_dword v41, v[28:29], off
	global_load_dword v42, v[10:11], off
	global_load_dword v44, v[8:9], off
	global_load_dword v46, v[6:7], off
	global_load_dword v48, v[4:5], off
	v_mad_i64_i32 v[4:5], s[0:1], s0, v90, v[2:3]
	s_or_b32 s0, s4, 34
	s_nop 0
	v_mad_i64_i32 v[6:7], s[0:1], s0, v90, v[2:3]
	s_or_b32 s0, s4, 36
	s_nop 0
	v_mad_i64_i32 v[8:9], s[0:1], s0, v90, v[2:3]
	s_or_b32 s0, s4, 38
	s_nop 0
	v_mad_i64_i32 v[10:11], s[0:1], s0, v90, v[2:3]
	s_or_b32 s0, s4, 40
	global_load_dword v39, v[30:31], off
	global_load_dword v37, v[32:33], off
	s_nop 0
	global_load_dword v35, v[34:35], off
	s_nop 0
	global_load_dword v33, v[74:75], off
	global_load_dword v34, v[10:11], off
	global_load_dword v36, v[8:9], off
	global_load_dword v38, v[6:7], off
	global_load_dword v40, v[4:5], off
	v_mad_i64_i32 v[4:5], s[0:1], s0, v90, v[2:3]
	s_or_b32 s0, s4, 42
	s_nop 0
	v_mad_i64_i32 v[6:7], s[0:1], s0, v90, v[2:3]
	s_or_b32 s0, s4, 44
	s_nop 0
	v_mad_i64_i32 v[8:9], s[0:1], s0, v90, v[2:3]
	s_or_b32 s0, s4, 46
	s_nop 0
	v_mad_i64_i32 v[10:11], s[0:1], s0, v90, v[2:3]
	s_or_b32 s0, s4, 48
	global_load_dword v31, v[78:79], off
	global_load_dword v29, v[80:81], off
	global_load_dword v27, v[82:83], off
	global_load_dword v25, v[84:85], off
	global_load_dword v26, v[10:11], off
	global_load_dword v28, v[8:9], off
	global_load_dword v30, v[6:7], off
	global_load_dword v32, v[4:5], off
	v_mad_i64_i32 v[4:5], s[0:1], s0, v90, v[2:3]
	s_or_b32 s0, s4, 50
	s_nop 0
	v_mad_i64_i32 v[6:7], s[0:1], s0, v90, v[2:3]
	s_or_b32 s0, s4, 52
	s_nop 0
	v_mad_i64_i32 v[74:75], s[0:1], s0, v90, v[2:3]
	s_or_b32 s0, s4, 54
	s_nop 0
	v_mad_i64_i32 v[78:79], s[0:1], s0, v90, v[2:3]
	s_or_b32 s0, s4, 56
	s_or_b32 s2, s4, 58
	s_or_b32 s3, s4, 60
	s_or_b32 s5, s4, 62
	global_load_dword v15, v[86:87], off
	global_load_dword v13, v[88:89], off
	global_load_dword v11, v[92:93], off
	global_load_dword v9, v[94:95], off
	global_load_dword v10, v[78:79], off
	global_load_dword v12, v[74:75], off
	global_load_dword v14, v[6:7], off
	global_load_dword v24, v[4:5], off
	v_mad_i64_i32 v[74:75], s[0:1], s0, v90, v[2:3]
	v_mad_i64_i32 v[78:79], s[0:1], s2, v90, v[2:3]
	v_mad_i64_i32 v[80:81], s[0:1], s3, v90, v[2:3]
	v_mad_i64_i32 v[82:83], s[0:1], s5, v90, v[2:3]
	global_load_dword v7, v[96:97], off
	global_load_dword v5, v[98:99], off
	global_load_dword v3, v[100:101], off
	global_load_dword v1, v[102:103], off
	global_load_dword v2, v[82:83], off
	global_load_dword v4, v[80:81], off
	global_load_dword v6, v[78:79], off
	global_load_dword v8, v[74:75], off
	v_cmp_ne_u32_e64 s[2:3], 1, v19
	s_andn2_b64 vcc, exec, s[24:25]
	s_ashr_i32 s5, s4, 31
	s_cbranch_vccnz .LBB0_120
	s_waitcnt vmcnt(62)
	v_mul_f32_e32 v22, 0x42800000, v180
	v_mov_b32_e32 v73, v181
	v_pk_mul_f32 v[74:75], v[72:73], v[22:23]
	s_cbranch_execnz .LBB0_28

; template <bool F8> __device__ __forceinline__ void transpose_item(const float* W, int K, int N, int ld, void* WTv, const float* kscale, float wscale, LAS float* scr, int item, int lane_) {
;     ...
;     for (int kk = 0; kk < 64; ++kk) { const float sc = (kscale ? kscale[k0 + kk] : 1.f) * wscale; scr[kk * 65 + lane] = v[kk] * sc; }
.LBB0_28:
	v_lshl_add_u32 v20, v0, 2, s29
	s_waitcnt vmcnt(62)
	v_mul_f32_e32 v22, v69, v75
	s_and_b64 vcc, exec, s[2:3]
	ds_write2_b32 v20, v74, v22 offset1:65
	s_cbranch_vccnz .LBB0_121
	s_waitcnt vmcnt(61)
	v_mul_f32_e32 v22, 0x42800000, v182
	v_mov_b32_e32 v71, v183
	v_pk_mul_f32 v[72:73], v[70:71], v[22:23]
	s_cbranch_execnz .LBB0_31

; template <bool F8> __device__ __forceinline__ void transpose_item(const float* W, int K, int N, int ld, void* WTv, const float* kscale, float wscale, LAS float* scr, int item, int lane_) {
;     ...
;     for (int kk = 0; kk < 64; ++kk) { const float sc = (kscale ? kscale[k0 + kk] : 1.f) * wscale; scr[kk * 65 + lane] = v[kk] * sc; }
.LBB0_31:
	s_waitcnt vmcnt(60)
	v_mul_f32_e32 v22, v67, v73
	s_and_b64 vcc, exec, s[2:3]
	ds_write2_b32 v20, v72, v22 offset0:130 offset1:195
	s_cbranch_vccnz .LBB0_122
	s_waitcnt vmcnt(59)
	v_mul_f32_e32 v22, 0x42800000, v184
	v_mov_b32_e32 v69, v185
	v_pk_mul_f32 v[70:71], v[68:69], v[22:23]
	s_cbranch_execnz .LBB0_34

; template <bool F8> __device__ __forceinline__ void transpose_item(const float* W, int K, int N, int ld, void* WTv, const float* kscale, float wscale, LAS float* scr, int item, int lane_) {
;     ...
;     for (int kk = 0; kk < 64; ++kk) { const float sc = (kscale ? kscale[k0 + kk] : 1.f) * wscale; scr[kk * 65 + lane] = v[kk] * sc; }
.LBB0_34:
	s_waitcnt vmcnt(58)
	v_mul_f32_e32 v22, v65, v71
	v_add_u32_e32 v65, 0x400, v20
	s_and_b64 vcc, exec, s[2:3]
	ds_write2_b32 v65, v70, v22 offset0:4 offset1:69
	s_cbranch_vccnz .LBB0_123
	s_waitcnt vmcnt(57)
	v_mul_f32_e32 v22, 0x42800000, v186
	v_mov_b32_e32 v67, v187
	v_pk_mul_f32 v[68:69], v[66:67], v[22:23]
	s_cbranch_execnz .LBB0_37

; template <bool F8> __device__ __forceinline__ void transpose_item(const float* W, int K, int N, int ld, void* WTv, const float* kscale, float wscale, LAS float* scr, int item, int lane_) {
;     ...
;     for (int kk = 0; kk < 64; ++kk) { const float sc = (kscale ? kscale[k0 + kk] : 1.f) * wscale; scr[kk * 65 + lane] = v[kk] * sc; }
.LBB0_37:
	s_waitcnt vmcnt(56)
	v_mul_f32_e32 v22, v63, v69
	s_and_b64 vcc, exec, s[2:3]
	ds_write2_b32 v65, v68, v22 offset0:134 offset1:199
	s_cbranch_vccnz .LBB0_124
	s_waitcnt vmcnt(55)
	v_mul_f32_e32 v22, 0x42800000, v188
	v_mov_b32_e32 v65, v189
	v_pk_mul_f32 v[66:67], v[64:65], v[22:23]
	s_cbranch_execnz .LBB0_40

; template <bool F8> __device__ __forceinline__ void transpose_item(const float* W, int K, int N, int ld, void* WTv, const float* kscale, float wscale, LAS float* scr, int item, int lane_) {
;     ...
;     for (int kk = 0; kk < 64; ++kk) { const float sc = (kscale ? kscale[k0 + kk] : 1.f) * wscale; scr[kk * 65 + lane] = v[kk] * sc; }
.LBB0_40:
	s_waitcnt vmcnt(54)
	v_mul_f32_e32 v22, v61, v67
	v_add_u32_e32 v63, 0x800, v20
	s_and_b64 vcc, exec, s[2:3]
	ds_write2_b32 v63, v66, v22 offset0:8 offset1:73
	s_cbranch_vccnz .LBB0_125
	s_waitcnt vmcnt(53)
	v_mul_f32_e32 v22, 0x42800000, v190
	v_mov_b32_e32 v61, v191
	v_pk_mul_f32 v[64:65], v[60:61], v[22:23]
	s_cbranch_execnz .LBB0_43

; template <bool F8> __device__ __forceinline__ void transpose_item(const float* W, int K, int N, int ld, void* WTv, const float* kscale, float wscale, LAS float* scr, int item, int lane_) {
;     ...
;     for (int kk = 0; kk < 64; ++kk) { const float sc = (kscale ? kscale[k0 + kk] : 1.f) * wscale; scr[kk * 65 + lane] = v[kk] * sc; }
.LBB0_43:
	s_waitcnt vmcnt(52)
	v_mul_f32_e32 v22, v57, v65
	s_and_b64 vcc, exec, s[2:3]
	ds_write2_b32 v63, v64, v22 offset0:138 offset1:203
	s_cbranch_vccnz .LBB0_126
	s_waitcnt vmcnt(51)
	v_mul_f32_e32 v22, 0x42800000, v192
	v_mov_b32_e32 v57, v193
	v_pk_mul_f32 v[60:61], v[56:57], v[22:23]
	s_cbranch_execnz .LBB0_46

; template <bool F8> __device__ __forceinline__ void transpose_item(const float* W, int K, int N, int ld, void* WTv, const float* kscale, float wscale, LAS float* scr, int item, int lane_) {
;     ...
;     for (int kk = 0; kk < 64; ++kk) { const float sc = (kscale ? kscale[k0 + kk] : 1.f) * wscale; scr[kk * 65 + lane] = v[kk] * sc; }
.LBB0_46:
	s_waitcnt vmcnt(50)
	v_mul_f32_e32 v22, v53, v61
	v_add_u32_e32 v61, 0xc00, v20
	s_and_b64 vcc, exec, s[2:3]
	ds_write2_b32 v61, v60, v22 offset0:12 offset1:77
	s_cbranch_vccnz .LBB0_127
	s_waitcnt vmcnt(49)
	v_mul_f32_e32 v22, 0x42800000, v194
	v_mov_b32_e32 v53, v195
	v_pk_mul_f32 v[56:57], v[52:53], v[22:23]
	s_cbranch_execnz .LBB0_49

; template <bool F8> __device__ __forceinline__ void transpose_item(const float* W, int K, int N, int ld, void* WTv, const float* kscale, float wscale, LAS float* scr, int item, int lane_) {
;     ...
;     for (int kk = 0; kk < 64; ++kk) { const float sc = (kscale ? kscale[k0 + kk] : 1.f) * wscale; scr[kk * 65 + lane] = v[kk] * sc; }
.LBB0_49:
	s_waitcnt vmcnt(48)
	v_mul_f32_e32 v22, v51, v57
	s_and_b64 vcc, exec, s[2:3]
	ds_write2_b32 v61, v56, v22 offset0:142 offset1:207
	s_cbranch_vccnz .LBB0_128
	s_waitcnt vmcnt(40)
	v_mul_f32_e32 v22, 0x42800000, v196
	v_mov_b32_e32 v63, v197
	v_pk_mul_f32 v[52:53], v[62:63], v[22:23]
	s_cbranch_execnz .LBB0_52

; template <bool F8> __device__ __forceinline__ void transpose_item(const float* W, int K, int N, int ld, void* WTv, const float* kscale, float wscale, LAS float* scr, int item, int lane_) {
;     ...
;     for (int kk = 0; kk < 64; ++kk) { const float sc = (kscale ? kscale[k0 + kk] : 1.f) * wscale; scr[kk * 65 + lane] = v[kk] * sc; }
.LBB0_52:
	s_waitcnt vmcnt(47)
	v_mul_f32_e32 v22, v59, v53
	v_add_u32_e32 v51, 0x1000, v20
	s_and_b64 vcc, exec, s[2:3]
	ds_write2_b32 v51, v52, v22 offset0:16 offset1:81
	s_cbranch_vccnz .LBB0_129
	s_waitcnt vmcnt(41)
	v_mul_f32_e32 v22, 0x42800000, v198
	v_mov_b32_e32 v59, v199
	v_pk_mul_f32 v[52:53], v[58:59], v[22:23]
	s_cbranch_execnz .LBB0_55

; template <bool F8> __device__ __forceinline__ void transpose_item(const float* W, int K, int N, int ld, void* WTv, const float* kscale, float wscale, LAS float* scr, int item, int lane_) {
;     ...
;     for (int kk = 0; kk < 64; ++kk) { const float sc = (kscale ? kscale[k0 + kk] : 1.f) * wscale; scr[kk * 65 + lane] = v[kk] * sc; }
.LBB0_55:
	s_waitcnt vmcnt(46)
	v_mul_f32_e32 v22, v55, v53
	s_and_b64 vcc, exec, s[2:3]
	ds_write2_b32 v51, v52, v22 offset0:146 offset1:211
	s_cbranch_vccnz .LBB0_130
	s_waitcnt vmcnt(42)
	v_mul_f32_e32 v22, 0x42800000, v200
	v_mov_b32_e32 v55, v201
	v_pk_mul_f32 v[52:53], v[54:55], v[22:23]
	s_cbranch_execnz .LBB0_58

; template <bool F8> __device__ __forceinline__ void transpose_item(const float* W, int K, int N, int ld, void* WTv, const float* kscale, float wscale, LAS float* scr, int item, int lane_) {
;     ...
;     for (int kk = 0; kk < 64; ++kk) { const float sc = (kscale ? kscale[k0 + kk] : 1.f) * wscale; scr[kk * 65 + lane] = v[kk] * sc; }
.LBB0_58:
	s_waitcnt vmcnt(45)
	v_mul_f32_e32 v22, v76, v53
	s_waitcnt vmcnt(42)
	v_add_u32_e32 v54, 0x1400, v20
	s_and_b64 vcc, exec, s[2:3]
	ds_write2_b32 v54, v52, v22 offset0:20 offset1:85
	s_cbranch_vccnz .LBB0_131
	s_waitcnt vmcnt(43)
	v_mul_f32_e32 v22, 0x42800000, v202
	v_mov_b32_e32 v51, v203
	v_pk_mul_f32 v[52:53], v[50:51], v[22:23]
	s_cbranch_execnz .LBB0_61

; template <bool F8> __device__ __forceinline__ void transpose_item(const float* W, int K, int N, int ld, void* WTv, const float* kscale, float wscale, LAS float* scr, int item, int lane_) {
;     ...
;     for (int kk = 0; kk < 64; ++kk) { const float sc = (kscale ? kscale[k0 + kk] : 1.f) * wscale; scr[kk * 65 + lane] = v[kk] * sc; }
.LBB0_61:
	v_mul_f32_e32 v22, v49, v53
	s_and_b64 vcc, exec, s[2:3]
	ds_write2_b32 v54, v52, v22 offset0:150 offset1:215
	s_cbranch_vccnz .LBB0_132
	s_waitcnt vmcnt(32)
	v_mul_f32_e32 v22, 0x42800000, v204
	v_mov_b32_e32 v49, v205
	v_pk_mul_f32 v[50:51], v[48:49], v[22:23]
	s_cbranch_execnz .LBB0_64

; template <bool F8> __device__ __forceinline__ void transpose_item(const float* W, int K, int N, int ld, void* WTv, const float* kscale, float wscale, LAS float* scr, int item, int lane_) {
;     ...
;     for (int kk = 0; kk < 64; ++kk) { const float sc = (kscale ? kscale[k0 + kk] : 1.f) * wscale; scr[kk * 65 + lane] = v[kk] * sc; }
.LBB0_64:
	s_waitcnt vmcnt(39)
	v_mul_f32_e32 v22, v47, v51
	v_add_u32_e32 v51, 0x1800, v20
	s_and_b64 vcc, exec, s[2:3]
	ds_write2_b32 v51, v50, v22 offset0:24 offset1:89
	s_cbranch_vccnz .LBB0_133
	s_waitcnt vmcnt(32)
	v_mul_f32_e32 v22, 0x42800000, v206
	v_mov_b32_e32 v47, v207
	v_pk_mul_f32 v[48:49], v[46:47], v[22:23]
	s_cbranch_execnz .LBB0_67

; template <bool F8> __device__ __forceinline__ void transpose_item(const float* W, int K, int N, int ld, void* WTv, const float* kscale, float wscale, LAS float* scr, int item, int lane_) {
;     ...
;     for (int kk = 0; kk < 64; ++kk) { const float sc = (kscale ? kscale[k0 + kk] : 1.f) * wscale; scr[kk * 65 + lane] = v[kk] * sc; }
.LBB0_67:
	s_waitcnt vmcnt(38)
	v_mul_f32_e32 v22, v45, v49
	s_and_b64 vcc, exec, s[2:3]
	s_waitcnt vmcnt(32)
	ds_write2_b32 v51, v48, v22 offset0:154 offset1:219
	s_cbranch_vccnz .LBB0_134
	s_waitcnt vmcnt(34)
	v_mul_f32_e32 v22, 0x42800000, v208
	v_mov_b32_e32 v45, v209
	v_pk_mul_f32 v[46:47], v[44:45], v[22:23]
	s_cbranch_execnz .LBB0_70

; template <bool F8> __device__ __forceinline__ void transpose_item(const float* W, int K, int N, int ld, void* WTv, const float* kscale, float wscale, LAS float* scr, int item, int lane_) {
;     ...
;     for (int kk = 0; kk < 64; ++kk) { const float sc = (kscale ? kscale[k0 + kk] : 1.f) * wscale; scr[kk * 65 + lane] = v[kk] * sc; }
.LBB0_70:
	v_mul_f32_e32 v22, v43, v47
	v_add_u32_e32 v47, 0x1c00, v20
	s_and_b64 vcc, exec, s[2:3]
	ds_write2_b32 v47, v46, v22 offset0:28 offset1:93
	s_cbranch_vccnz .LBB0_135
	s_waitcnt vmcnt(35)
	v_mul_f32_e32 v22, 0x42800000, v210
	v_mov_b32_e32 v43, v211
	v_pk_mul_f32 v[44:45], v[42:43], v[22:23]
	s_cbranch_execnz .LBB0_73

; template <bool F8> __device__ __forceinline__ void transpose_item(const float* W, int K, int N, int ld, void* WTv, const float* kscale, float wscale, LAS float* scr, int item, int lane_) {
;     ...
;     for (int kk = 0; kk < 64; ++kk) { const float sc = (kscale ? kscale[k0 + kk] : 1.f) * wscale; scr[kk * 65 + lane] = v[kk] * sc; }
.LBB0_73:
	v_mul_f32_e32 v22, v41, v45
	s_and_b64 vcc, exec, s[2:3]
	ds_write2_b32 v47, v44, v22 offset0:158 offset1:223
	s_cbranch_vccnz .LBB0_136
	s_waitcnt vmcnt(24)
	v_mul_f32_e32 v22, 0x42800000, v212
	v_mov_b32_e32 v41, v213
	v_pk_mul_f32 v[42:43], v[40:41], v[22:23]
	s_cbranch_execnz .LBB0_76

; template <bool F8> __device__ __forceinline__ void transpose_item(const float* W, int K, int N, int ld, void* WTv, const float* kscale, float wscale, LAS float* scr, int item, int lane_) {
;     ...
;     for (int kk = 0; kk < 64; ++kk) { const float sc = (kscale ? kscale[k0 + kk] : 1.f) * wscale; scr[kk * 65 + lane] = v[kk] * sc; }
.LBB0_76:
	s_waitcnt vmcnt(31)
	v_mul_f32_e32 v22, v39, v43
	v_add_u32_e32 v43, 0x2000, v20
	s_and_b64 vcc, exec, s[2:3]
	ds_write2_b32 v43, v42, v22 offset0:32 offset1:97
	s_cbranch_vccnz .LBB0_137
	s_waitcnt vmcnt(24)
	v_mul_f32_e32 v22, 0x42800000, v214
	v_mov_b32_e32 v39, v215
	v_pk_mul_f32 v[40:41], v[38:39], v[22:23]
	s_cbranch_execnz .LBB0_79

; template <bool F8> __device__ __forceinline__ void transpose_item(const float* W, int K, int N, int ld, void* WTv, const float* kscale, float wscale, LAS float* scr, int item, int lane_) {
;     ...
;     for (int kk = 0; kk < 64; ++kk) { const float sc = (kscale ? kscale[k0 + kk] : 1.f) * wscale; scr[kk * 65 + lane] = v[kk] * sc; }
.LBB0_79:
	s_waitcnt vmcnt(30)
	v_mul_f32_e32 v22, v37, v41
	s_and_b64 vcc, exec, s[2:3]
	s_waitcnt vmcnt(24)
	ds_write2_b32 v43, v40, v22 offset0:162 offset1:227
	s_cbranch_vccnz .LBB0_138
	s_waitcnt vmcnt(26)
	v_mul_f32_e32 v22, 0x42800000, v216
	v_mov_b32_e32 v37, v217
	v_pk_mul_f32 v[38:39], v[36:37], v[22:23]
	s_cbranch_execnz .LBB0_82

; template <bool F8> __device__ __forceinline__ void transpose_item(const float* W, int K, int N, int ld, void* WTv, const float* kscale, float wscale, LAS float* scr, int item, int lane_) {
;     ...
;     for (int kk = 0; kk < 64; ++kk) { const float sc = (kscale ? kscale[k0 + kk] : 1.f) * wscale; scr[kk * 65 + lane] = v[kk] * sc; }
.LBB0_82:
	v_mul_f32_e32 v22, v35, v39
	v_add_u32_e32 v39, 0x2400, v20
	s_and_b64 vcc, exec, s[2:3]
	ds_write2_b32 v39, v38, v22 offset0:36 offset1:101
	s_cbranch_vccnz .LBB0_139
	s_waitcnt vmcnt(27)
	v_mul_f32_e32 v22, 0x42800000, v218
	v_mov_b32_e32 v35, v219
	v_pk_mul_f32 v[36:37], v[34:35], v[22:23]
	s_cbranch_execnz .LBB0_85

; template <bool F8> __device__ __forceinline__ void transpose_item(const float* W, int K, int N, int ld, void* WTv, const float* kscale, float wscale, LAS float* scr, int item, int lane_) {
;     ...
;     for (int kk = 0; kk < 64; ++kk) { const float sc = (kscale ? kscale[k0 + kk] : 1.f) * wscale; scr[kk * 65 + lane] = v[kk] * sc; }
.LBB0_85:
	v_mul_f32_e32 v22, v33, v37
	s_and_b64 vcc, exec, s[2:3]
	ds_write2_b32 v39, v36, v22 offset0:166 offset1:231
	s_cbranch_vccnz .LBB0_140
	s_waitcnt vmcnt(16)
	v_mul_f32_e32 v22, 0x42800000, v220
	v_mov_b32_e32 v33, v221
	v_pk_mul_f32 v[34:35], v[32:33], v[22:23]
	s_cbranch_execnz .LBB0_88

; template <bool F8> __device__ __forceinline__ void transpose_item(const float* W, int K, int N, int ld, void* WTv, const float* kscale, float wscale, LAS float* scr, int item, int lane_) {
;     ...
;     for (int kk = 0; kk < 64; ++kk) { const float sc = (kscale ? kscale[k0 + kk] : 1.f) * wscale; scr[kk * 65 + lane] = v[kk] * sc; }
.LBB0_88:
	s_waitcnt vmcnt(23)
	v_mul_f32_e32 v22, v31, v35
	v_add_u32_e32 v35, 0x2800, v20
	s_and_b64 vcc, exec, s[2:3]
	ds_write2_b32 v35, v34, v22 offset0:40 offset1:105
	s_cbranch_vccnz .LBB0_141
	s_waitcnt vmcnt(16)
	v_mul_f32_e32 v22, 0x42800000, v222
	v_mov_b32_e32 v31, v223
	v_pk_mul_f32 v[32:33], v[30:31], v[22:23]
	s_cbranch_execnz .LBB0_91

; template <bool F8> __device__ __forceinline__ void transpose_item(const float* W, int K, int N, int ld, void* WTv, const float* kscale, float wscale, LAS float* scr, int item, int lane_) {
;     ...
;     for (int kk = 0; kk < 64; ++kk) { const float sc = (kscale ? kscale[k0 + kk] : 1.f) * wscale; scr[kk * 65 + lane] = v[kk] * sc; }
.LBB0_91:
	s_waitcnt vmcnt(22)
	v_mul_f32_e32 v22, v29, v33
	s_and_b64 vcc, exec, s[2:3]
	s_waitcnt vmcnt(16)
	ds_write2_b32 v35, v32, v22 offset0:170 offset1:235
	s_cbranch_vccnz .LBB0_142
	s_waitcnt vmcnt(18)
	v_mul_f32_e32 v22, 0x42800000, v224
	v_mov_b32_e32 v29, v225
	v_pk_mul_f32 v[30:31], v[28:29], v[22:23]
	s_cbranch_execnz .LBB0_94

; template <bool F8> __device__ __forceinline__ void transpose_item(const float* W, int K, int N, int ld, void* WTv, const float* kscale, float wscale, LAS float* scr, int item, int lane_) {
;     ...
;     for (int kk = 0; kk < 64; ++kk) { const float sc = (kscale ? kscale[k0 + kk] : 1.f) * wscale; scr[kk * 65 + lane] = v[kk] * sc; }
.LBB0_94:
	v_mul_f32_e32 v22, v27, v31
	v_add_u32_e32 v31, 0x2c00, v20
	s_and_b64 vcc, exec, s[2:3]
	ds_write2_b32 v31, v30, v22 offset0:44 offset1:109
	s_cbranch_vccnz .LBB0_143
	s_waitcnt vmcnt(19)
	v_mul_f32_e32 v22, 0x42800000, v226
	v_mov_b32_e32 v27, v227
	v_pk_mul_f32 v[28:29], v[26:27], v[22:23]
	s_cbranch_execnz .LBB0_97

; template <bool F8> __device__ __forceinline__ void transpose_item(const float* W, int K, int N, int ld, void* WTv, const float* kscale, float wscale, LAS float* scr, int item, int lane_) {
;     ...
;     for (int kk = 0; kk < 64; ++kk) { const float sc = (kscale ? kscale[k0 + kk] : 1.f) * wscale; scr[kk * 65 + lane] = v[kk] * sc; }
.LBB0_97:
	v_mul_f32_e32 v22, v25, v29
	s_and_b64 vcc, exec, s[2:3]
	ds_write2_b32 v31, v28, v22 offset0:174 offset1:239
	s_cbranch_vccnz .LBB0_144
	s_waitcnt vmcnt(8)
	v_mul_f32_e32 v22, 0x42800000, v228
	v_mov_b32_e32 v25, v229
	v_pk_mul_f32 v[26:27], v[24:25], v[22:23]
	s_cbranch_execnz .LBB0_100

; template <bool F8> __device__ __forceinline__ void transpose_item(const float* W, int K, int N, int ld, void* WTv, const float* kscale, float wscale, LAS float* scr, int item, int lane_) {
;     ...
;     for (int kk = 0; kk < 64; ++kk) { const float sc = (kscale ? kscale[k0 + kk] : 1.f) * wscale; scr[kk * 65 + lane] = v[kk] * sc; }
.LBB0_100:
	s_waitcnt vmcnt(15)
	v_mul_f32_e32 v15, v15, v27
	v_add_u32_e32 v27, 0x3000, v20
	s_and_b64 vcc, exec, s[2:3]
	ds_write2_b32 v27, v26, v15 offset0:48 offset1:113
	s_cbranch_vccnz .LBB0_145
	s_waitcnt vmcnt(8)
	v_mul_f32_e32 v22, 0x42800000, v230
	v_mov_b32_e32 v15, v231
	v_pk_mul_f32 v[24:25], v[14:15], v[22:23]
	s_cbranch_execnz .LBB0_103

; template <bool F8> __device__ __forceinline__ void transpose_item(const float* W, int K, int N, int ld, void* WTv, const float* kscale, float wscale, LAS float* scr, int item, int lane_) {
;     ...
;     for (int kk = 0; kk < 64; ++kk) { const float sc = (kscale ? kscale[k0 + kk] : 1.f) * wscale; scr[kk * 65 + lane] = v[kk] * sc; }
.LBB0_103:
	s_waitcnt vmcnt(14)
	v_mul_f32_e32 v13, v13, v25
	s_and_b64 vcc, exec, s[2:3]
	s_waitcnt vmcnt(8)
	ds_write2_b32 v27, v24, v13 offset0:178 offset1:243
	s_cbranch_vccnz .LBB0_146
	s_waitcnt vmcnt(10)
	v_mul_f32_e32 v22, 0x42800000, v232
	v_mov_b32_e32 v13, v233
	v_pk_mul_f32 v[14:15], v[12:13], v[22:23]
	s_cbranch_execnz .LBB0_106

; template <bool F8> __device__ __forceinline__ void transpose_item(const float* W, int K, int N, int ld, void* WTv, const float* kscale, float wscale, LAS float* scr, int item, int lane_) {
;     ...
;     for (int kk = 0; kk < 64; ++kk) { const float sc = (kscale ? kscale[k0 + kk] : 1.f) * wscale; scr[kk * 65 + lane] = v[kk] * sc; }
.LBB0_106:
	v_mul_f32_e32 v11, v11, v15
	v_add_u32_e32 v15, 0x3400, v20
	s_and_b64 vcc, exec, s[2:3]
	ds_write2_b32 v15, v14, v11 offset0:52 offset1:117
	s_cbranch_vccnz .LBB0_147
	s_waitcnt vmcnt(11)
	v_mul_f32_e32 v22, 0x42800000, v234
	v_mov_b32_e32 v11, v235
	v_pk_mul_f32 v[12:13], v[10:11], v[22:23]
	s_cbranch_execnz .LBB0_109

; template <bool F8> __device__ __forceinline__ void transpose_item(const float* W, int K, int N, int ld, void* WTv, const float* kscale, float wscale, LAS float* scr, int item, int lane_) {
;     ...
;     for (int kk = 0; kk < 64; ++kk) { const float sc = (kscale ? kscale[k0 + kk] : 1.f) * wscale; scr[kk * 65 + lane] = v[kk] * sc; }
.LBB0_109:
	v_mul_f32_e32 v9, v9, v13
	s_and_b64 vcc, exec, s[2:3]
	ds_write2_b32 v15, v12, v9 offset0:182 offset1:247
	s_cbranch_vccnz .LBB0_148
	s_waitcnt vmcnt(0)
	v_mul_f32_e32 v22, 0x42800000, v236
	v_mov_b32_e32 v9, v237
	v_pk_mul_f32 v[10:11], v[8:9], v[22:23]
	s_cbranch_execnz .LBB0_112

; template <bool F8> __device__ __forceinline__ void transpose_item(const float* W, int K, int N, int ld, void* WTv, const float* kscale, float wscale, LAS float* scr, int item, int lane_) {
;     ...
;     for (int kk = 0; kk < 64; ++kk) { const float sc = (kscale ? kscale[k0 + kk] : 1.f) * wscale; scr[kk * 65 + lane] = v[kk] * sc; }
.LBB0_112:
	s_waitcnt vmcnt(7)
	v_mul_f32_e32 v7, v7, v11
	v_add_u32_e32 v11, 0x3800, v20
	s_and_b64 vcc, exec, s[2:3]
	ds_write2_b32 v11, v10, v7 offset0:56 offset1:121
	s_cbranch_vccnz .LBB0_149
	s_waitcnt vmcnt(0)
	v_mul_f32_e32 v22, 0x42800000, v238
	v_mov_b32_e32 v7, v239
	v_pk_mul_f32 v[8:9], v[6:7], v[22:23]
	s_cbranch_execnz .LBB0_115

; template <bool F8> __device__ __forceinline__ void transpose_item(const float* W, int K, int N, int ld, void* WTv, const float* kscale, float wscale, LAS float* scr, int item, int lane_) {
;     ...
;     for (int kk = 0; kk < 64; ++kk) { const float sc = (kscale ? kscale[k0 + kk] : 1.f) * wscale; scr[kk * 65 + lane] = v[kk] * sc; }
.LBB0_115:
	s_waitcnt vmcnt(6)
	v_mul_f32_e32 v5, v5, v9
	s_and_b64 vcc, exec, s[2:3]
	s_waitcnt vmcnt(0)
	ds_write2_b32 v11, v8, v5 offset0:186 offset1:251
	s_cbranch_vccnz .LBB0_150
	s_waitcnt vmcnt(2)
	v_mul_f32_e32 v22, 0x42800000, v240
	v_mov_b32_e32 v5, v241
	v_pk_mul_f32 v[6:7], v[4:5], v[22:23]
	s_cbranch_execnz .LBB0_118

; template <bool F8> __device__ __forceinline__ void transpose_item(const float* W, int K, int N, int ld, void* WTv, const float* kscale, float wscale, LAS float* scr, int item, int lane_) {
;     ...
;     for (int kk = 0; kk < 64; ++kk) { const float sc = (kscale ? kscale[k0 + kk] : 1.f) * wscale; scr[kk * 65 + lane] = v[kk] * sc; }
.LBB0_118:
	v_mul_f32_e32 v3, v3, v7
	v_add_u32_e32 v7, 0x3c00, v20
	s_and_b64 vcc, exec, s[2:3]
	ds_write2_b32 v7, v6, v3 offset0:60 offset1:125
	s_cbranch_vccnz .LBB0_151
	s_waitcnt vmcnt(3)
	v_mul_f32_e32 v22, 0x42800000, v242
	v_mov_b32_e32 v3, v243
	v_pk_mul_f32 v[4:5], v[2:3], v[22:23]
	s_cbranch_execnz .LBB0_24
	s_branch .LBB0_152

; template <bool F8> __device__ __forceinline__ void transpose_item(const float* W, int K, int N, int ld, void* WTv, const float* kscale, float wscale, LAS float* scr, int item, int lane_) {
;     ...
;     const int nblk = N / 64, kb = item / nblk, nb = item % nblk, k0 = 64 * kb, n0 = 64 * nb;
;     float v[64];
; #pragma unroll
;     for (int kk = 0; kk < 64; ++kk) v[kk] = W[(size_t)(k0 + kk) * ld + n0 + lane];
; #pragma unroll
;     for (int kk = 0; kk < 64; ++kk) { const float sc = (kscale ? kscale[k0 + kk] : 1.f) * wscale; scr[kk * 65 + lane] = v[kk] * sc; }
.LBB0_156:
	s_mul_hi_i32 s0, s15, 0x2aaaaaab
	s_lshr_b32 s1, s0, 31
	s_ashr_i32 s16, s0, 4
	s_add_i32 s16, s16, s1
	s_mul_i32 s0, s16, 0xffffe800
	s_add_i32 s0, s14, s0
	s_ashr_i32 s1, s0, 31
	s_lshl_b32 s4, s16, 6
	s_lshl_b64 s[0:1], s[0:1], 2
	v_mov_b32_e32 v0, v18
	s_add_u32 s0, s12, s0
	s_addc_u32 s1, s13, s1
	v_ashrrev_i32_e32 v1, 31, v0
	v_lshl_add_u64 v[2:3], v[0:1], 2, s[0:1]
	v_mad_i64_i32 v[4:5], s[0:1], s4, v90, v[2:3]
	s_or_b32 s0, s4, 1
	s_nop 0
	v_mad_i64_i32 v[6:7], s[0:1], s0, v90, v[2:3]
	s_or_b32 s0, s4, 2
	s_nop 0
	v_mad_i64_i32 v[8:9], s[0:1], s0, v90, v[2:3]
	s_or_b32 s0, s4, 3
	s_nop 0
	v_mad_i64_i32 v[10:11], s[0:1], s0, v90, v[2:3]
	s_or_b32 s0, s4, 4
	s_nop 0
	v_mad_i64_i32 v[12:13], s[0:1], s0, v90, v[2:3]
	s_or_b32 s0, s4, 5
	s_nop 0
	v_mad_i64_i32 v[14:15], s[0:1], s0, v90, v[2:3]
	s_or_b32 s0, s4, 6
	s_nop 0
	v_mad_i64_i32 v[24:25], s[0:1], s0, v90, v[2:3]
	s_or_b32 s0, s4, 7
	s_nop 0
	v_mad_i64_i32 v[26:27], s[0:1], s0, v90, v[2:3]
	s_or_b32 s0, s4, 8
	s_cmp_lg_u64 s[6:7], 0
	s_cbranch_scc0 .Lks_skip_lbb0_156
	s_lshl_b32 s20, s4, 2
	s_add_u32 s20, s6, s20
	s_addc_u32 s21, s7, 0
	global_load_dwordx4 v[180:183], v21, s[20:21]
	global_load_dwordx4 v[184:187], v21, s[20:21] offset:16
	global_load_dwordx4 v[188:191], v21, s[20:21] offset:32
	global_load_dwordx4 v[192:195], v21, s[20:21] offset:48
	global_load_dwordx4 v[196:199], v21, s[20:21] offset:64
	global_load_dwordx4 v[200:203], v21, s[20:21] offset:80
	global_load_dwordx4 v[204:207], v21, s[20:21] offset:96
	global_load_dwordx4 v[208:211], v21, s[20:21] offset:112
	global_load_dwordx4 v[212:215], v21, s[20:21] offset:128
	global_load_dwordx4 v[216:219], v21, s[20:21] offset:144
	global_load_dwordx4 v[220:223], v21, s[20:21] offset:160
	global_load_dwordx4 v[224:227], v21, s[20:21] offset:176
	global_load_dwordx4 v[228:231], v21, s[20:21] offset:192
	global_load_dwordx4 v[232:235], v21, s[20:21] offset:208
	global_load_dwordx4 v[236:239], v21, s[20:21] offset:224
	global_load_dwordx4 v[240:243], v21, s[20:21] offset:240
; template <bool F8> __device__ __forceinline__ void transpose_item(const float* W, int K, int N, int ld, void* WTv, const float* kscale, float wscale, LAS float* scr, int item, int lane_) {
;     ...
;     for (int kk = 0; kk < 64; ++kk) v[kk] = W[(size_t)(k0 + kk) * ld + n0 + lane];
; #pragma unroll
;     for (int kk = 0; kk < 64; ++kk) { const float sc = (kscale ? kscale[k0 + kk] : 1.f) * wscale; scr[kk * 65 + lane] = v[kk] * sc; }
.Lks_skip_lbb0_156:
	global_load_dword v72, v[4:5], off
	global_load_dword v69, v[6:7], off
	global_load_dword v70, v[8:9], off
	global_load_dword v67, v[10:11], off
	global_load_dword v68, v[12:13], off
	global_load_dword v65, v[14:15], off
	global_load_dword v66, v[24:25], off
	global_load_dword v63, v[26:27], off
	v_mad_i64_i32 v[4:5], s[0:1], s0, v90, v[2:3]
	s_or_b32 s0, s4, 9
	s_nop 0
	v_mad_i64_i32 v[6:7], s[0:1], s0, v90, v[2:3]
	s_or_b32 s0, s4, 10
	s_nop 0
	v_mad_i64_i32 v[8:9], s[0:1], s0, v90, v[2:3]
	s_or_b32 s0, s4, 11
	s_nop 0
	v_mad_i64_i32 v[10:11], s[0:1], s0, v90, v[2:3]
	s_or_b32 s0, s4, 12
	s_nop 0
	v_mad_i64_i32 v[12:13], s[0:1], s0, v90, v[2:3]
	s_or_b32 s0, s4, 13
	s_nop 0
	v_mad_i64_i32 v[14:15], s[0:1], s0, v90, v[2:3]
	s_or_b32 s0, s4, 14
	s_nop 0
	v_mad_i64_i32 v[24:25], s[0:1], s0, v90, v[2:3]
	s_or_b32 s0, s4, 15
	s_nop 0
	v_mad_i64_i32 v[26:27], s[0:1], s0, v90, v[2:3]
	s_or_b32 s0, s4, 16
	global_load_dword v64, v[4:5], off
	global_load_dword v61, v[6:7], off
	global_load_dword v62, v[8:9], off
	global_load_dword v59, v[10:11], off
	global_load_dword v60, v[12:13], off
	global_load_dword v57, v[14:15], off
	global_load_dword v58, v[24:25], off
	global_load_dword v55, v[26:27], off
	v_mad_i64_i32 v[4:5], s[0:1], s0, v90, v[2:3]
	s_or_b32 s0, s4, 17
	s_nop 0
	v_mad_i64_i32 v[6:7], s[0:1], s0, v90, v[2:3]
	s_or_b32 s0, s4, 18
	s_nop 0
	v_mad_i64_i32 v[8:9], s[0:1], s0, v90, v[2:3]
	s_or_b32 s0, s4, 19
	s_nop 0
	v_mad_i64_i32 v[10:11], s[0:1], s0, v90, v[2:3]
	s_or_b32 s0, s4, 20
	s_nop 0
	v_mad_i64_i32 v[12:13], s[0:1], s0, v90, v[2:3]
	s_or_b32 s0, s4, 21
	s_nop 0
	v_mad_i64_i32 v[14:15], s[0:1], s0, v90, v[2:3]
	s_or_b32 s0, s4, 22
	s_nop 0
	v_mad_i64_i32 v[24:25], s[0:1], s0, v90, v[2:3]
	s_or_b32 s0, s4, 23
	s_nop 0
	v_mad_i64_i32 v[26:27], s[0:1], s0, v90, v[2:3]
	s_or_b32 s0, s4, 24
	global_load_dword v56, v[4:5], off
	global_load_dword v53, v[6:7], off
	global_load_dword v54, v[8:9], off
	global_load_dword v51, v[10:11], off
	global_load_dword v52, v[12:13], off
	global_load_dword v49, v[14:15], off
	global_load_dword v50, v[24:25], off
	global_load_dword v47, v[26:27], off
	v_mad_i64_i32 v[4:5], s[0:1], s0, v90, v[2:3]
	s_or_b32 s0, s4, 25
	s_nop 0
	v_mad_i64_i32 v[6:7], s[0:1], s0, v90, v[2:3]
	s_or_b32 s0, s4, 26
	s_nop 0
	v_mad_i64_i32 v[8:9], s[0:1], s0, v90, v[2:3]
	s_or_b32 s0, s4, 27
	s_nop 0
	v_mad_i64_i32 v[10:11], s[0:1], s0, v90, v[2:3]
	s_or_b32 s0, s4, 28
	s_nop 0
	v_mad_i64_i32 v[12:13], s[0:1], s0, v90, v[2:3]
	s_or_b32 s0, s4, 29
	s_nop 0
	v_mad_i64_i32 v[14:15], s[0:1], s0, v90, v[2:3]
	s_or_b32 s0, s4, 30
	s_nop 0
	v_mad_i64_i32 v[24:25], s[0:1], s0, v90, v[2:3]
	s_or_b32 s0, s4, 31
	s_nop 0
	v_mad_i64_i32 v[26:27], s[0:1], s0, v90, v[2:3]
	s_or_b32 s0, s4, 32
	global_load_dword v48, v[4:5], off
	global_load_dword v45, v[6:7], off
	global_load_dword v46, v[8:9], off
	global_load_dword v43, v[10:11], off
	global_load_dword v42, v[12:13], off
	global_load_dword v39, v[14:15], off
	global_load_dword v38, v[24:25], off
	global_load_dword v37, v[26:27], off
	v_mad_i64_i32 v[4:5], s[0:1], s0, v90, v[2:3]
	s_or_b32 s0, s4, 33
	s_nop 0
	v_mad_i64_i32 v[6:7], s[0:1], s0, v90, v[2:3]
	s_or_b32 s0, s4, 35
	s_nop 0
	v_mad_i64_i32 v[8:9], s[0:1], s0, v90, v[2:3]
	s_or_b32 s0, s4, 37
	s_nop 0
	v_mad_i64_i32 v[10:11], s[0:1], s0, v90, v[2:3]
	s_or_b32 s0, s4, 39
	s_nop 0
	v_mad_i64_i32 v[12:13], s[0:1], s0, v90, v[2:3]
	s_or_b32 s0, s4, 41
	s_nop 0
	v_mad_i64_i32 v[14:15], s[0:1], s0, v90, v[2:3]
	s_or_b32 s0, s4, 43
	s_nop 0
	v_mad_i64_i32 v[24:25], s[0:1], s0, v90, v[2:3]
	s_or_b32 s0, s4, 45
	s_nop 0
	v_mad_i64_i32 v[26:27], s[0:1], s0, v90, v[2:3]
	s_or_b32 s0, s4, 47
	s_nop 0
	v_mad_i64_i32 v[74:75], s[0:1], s0, v90, v[2:3]
	s_or_b32 s0, s4, 49
	s_nop 0
	v_mad_i64_i32 v[78:79], s[0:1], s0, v90, v[2:3]
	s_or_b32 s0, s4, 51
	s_nop 0
	v_mad_i64_i32 v[80:81], s[0:1], s0, v90, v[2:3]
	s_or_b32 s0, s4, 53
	s_nop 0
	v_mad_i64_i32 v[82:83], s[0:1], s0, v90, v[2:3]
	s_or_b32 s0, s4, 55
	s_nop 0
	v_mad_i64_i32 v[84:85], s[0:1], s0, v90, v[2:3]
	s_or_b32 s0, s4, 57
	s_nop 0
	v_mad_i64_i32 v[86:87], s[0:1], s0, v90, v[2:3]
	s_or_b32 s0, s4, 59
	s_nop 0
	v_mad_i64_i32 v[88:89], s[0:1], s0, v90, v[2:3]
	s_or_b32 s0, s4, 61
	s_nop 0
	v_mad_i64_i32 v[92:93], s[0:1], s0, v90, v[2:3]
	s_or_b32 s2, s4, 34
	s_or_b32 s0, s4, 63
	v_mad_i64_i32 v[94:95], s[0:1], s0, v90, v[2:3]
	v_mad_i64_i32 v[28:29], s[0:1], s2, v90, v[2:3]
	s_or_b32 s0, s4, 36
	s_nop 0
	v_mad_i64_i32 v[30:31], s[0:1], s0, v90, v[2:3]
	s_or_b32 s0, s4, 38
	s_nop 0
	v_mad_i64_i32 v[96:97], s[0:1], s0, v90, v[2:3]
	s_or_b32 s0, s4, 40
	global_load_dword v41, v[6:7], off
	global_load_dword v76, v[8:9], off
	global_load_dword v35, v[10:11], off
	global_load_dword v33, v[12:13], off
	global_load_dword v34, v[96:97], off
	global_load_dword v36, v[30:31], off
	global_load_dword v40, v[28:29], off
	global_load_dword v44, v[4:5], off
	v_mad_i64_i32 v[4:5], s[0:1], s0, v90, v[2:3]
	s_or_b32 s0, s4, 42
	s_nop 0
	v_mad_i64_i32 v[6:7], s[0:1], s0, v90, v[2:3]
	s_or_b32 s0, s4, 44
	s_nop 0
	v_mad_i64_i32 v[8:9], s[0:1], s0, v90, v[2:3]
	s_or_b32 s0, s4, 46
	s_nop 0
	v_mad_i64_i32 v[10:11], s[0:1], s0, v90, v[2:3]
	s_or_b32 s0, s4, 48
	global_load_dword v31, v[14:15], off
	global_load_dword v29, v[24:25], off
	s_nop 0
	global_load_dword v27, v[26:27], off
	s_nop 0
	global_load_dword v25, v[74:75], off
	global_load_dword v26, v[10:11], off
	global_load_dword v28, v[8:9], off
	global_load_dword v30, v[6:7], off
	global_load_dword v32, v[4:5], off
	v_mad_i64_i32 v[4:5], s[0:1], s0, v90, v[2:3]
	s_or_b32 s0, s4, 50
	s_nop 0
	v_mad_i64_i32 v[6:7], s[0:1], s0, v90, v[2:3]
	s_or_b32 s0, s4, 52
	s_nop 0
	v_mad_i64_i32 v[74:75], s[0:1], s0, v90, v[2:3]
	s_or_b32 s0, s4, 54
	s_nop 0
	v_mad_i64_i32 v[96:97], s[0:1], s0, v90, v[2:3]
	s_or_b32 s0, s4, 56
	s_or_b32 s2, s4, 58
	s_or_b32 s3, s4, 60
	s_or_b32 s5, s4, 62
	global_load_dword v15, v[78:79], off
	global_load_dword v13, v[80:81], off
	global_load_dword v11, v[82:83], off
	global_load_dword v9, v[84:85], off
	global_load_dword v10, v[96:97], off
	global_load_dword v12, v[74:75], off
	global_load_dword v14, v[6:7], off
	global_load_dword v24, v[4:5], off
	v_mad_i64_i32 v[74:75], s[0:1], s0, v90, v[2:3]
	v_mad_i64_i32 v[78:79], s[0:1], s2, v90, v[2:3]
	v_mad_i64_i32 v[80:81], s[0:1], s3, v90, v[2:3]
	v_mad_i64_i32 v[82:83], s[0:1], s5, v90, v[2:3]
	global_load_dword v7, v[86:87], off
	global_load_dword v5, v[88:89], off
	global_load_dword v3, v[92:93], off
	global_load_dword v1, v[94:95], off
	global_load_dword v2, v[82:83], off
	global_load_dword v4, v[80:81], off
	global_load_dword v6, v[78:79], off
	global_load_dword v8, v[74:75], off
	v_cmp_ne_u32_e64 s[2:3], 1, v19
	s_andn2_b64 vcc, exec, s[24:25]
	s_ashr_i32 s5, s4, 31
	s_cbranch_vccnz .LBB0_251
	s_waitcnt vmcnt(62)
	v_mul_f32_e32 v22, 0x42800000, v180
	v_mov_b32_e32 v73, v181
	v_pk_mul_f32 v[74:75], v[72:73], v[22:23]
	s_cbranch_execnz .LBB0_159

; template <bool F8> __device__ __forceinline__ void transpose_item(const float* W, int K, int N, int ld, void* WTv, const float* kscale, float wscale, LAS float* scr, int item, int lane_) {
;     ...
;     for (int kk = 0; kk < 64; ++kk) { const float sc = (kscale ? kscale[k0 + kk] : 1.f) * wscale; scr[kk * 65 + lane] = v[kk] * sc; }
.LBB0_171:
	s_waitcnt vmcnt(54)
	v_mul_f32_e32 v22, v61, v67
	v_add_u32_e32 v61, 0x800, v20
	s_and_b64 vcc, exec, s[2:3]
	ds_write2_b32 v61, v66, v22 offset0:8 offset1:73
	s_cbranch_vccnz .LBB0_256
	s_waitcnt vmcnt(53)
	v_mul_f32_e32 v22, 0x42800000, v190
	v_mov_b32_e32 v63, v191
	v_pk_mul_f32 v[64:65], v[62:63], v[22:23]
	s_cbranch_execnz .LBB0_174

; template <bool F8> __device__ __forceinline__ void transpose_item(const float* W, int K, int N, int ld, void* WTv, const float* kscale, float wscale, LAS float* scr, int item, int lane_) {
;     ...
;     for (int kk = 0; kk < 64; ++kk) { const float sc = (kscale ? kscale[k0 + kk] : 1.f) * wscale; scr[kk * 65 + lane] = v[kk] * sc; }
.LBB0_174:
	s_waitcnt vmcnt(52)
	v_mul_f32_e32 v22, v59, v65
	s_and_b64 vcc, exec, s[2:3]
	ds_write2_b32 v61, v64, v22 offset0:138 offset1:203
	s_cbranch_vccnz .LBB0_257
	s_waitcnt vmcnt(51)
	v_mul_f32_e32 v22, 0x42800000, v192
	v_mov_b32_e32 v61, v193
	v_pk_mul_f32 v[62:63], v[60:61], v[22:23]
	s_cbranch_execnz .LBB0_177

; template <bool F8> __device__ __forceinline__ void transpose_item(const float* W, int K, int N, int ld, void* WTv, const float* kscale, float wscale, LAS float* scr, int item, int lane_) {
;     ...
;     for (int kk = 0; kk < 64; ++kk) { const float sc = (kscale ? kscale[k0 + kk] : 1.f) * wscale; scr[kk * 65 + lane] = v[kk] * sc; }
.LBB0_177:
	s_waitcnt vmcnt(50)
	v_mul_f32_e32 v22, v57, v63
	v_add_u32_e32 v57, 0xc00, v20
	s_and_b64 vcc, exec, s[2:3]
	ds_write2_b32 v57, v62, v22 offset0:12 offset1:77
	s_cbranch_vccnz .LBB0_258
	s_waitcnt vmcnt(49)
	v_mul_f32_e32 v22, 0x42800000, v194
	v_mov_b32_e32 v59, v195
	v_pk_mul_f32 v[60:61], v[58:59], v[22:23]
	s_cbranch_execnz .LBB0_180

; template <bool F8> __device__ __forceinline__ void transpose_item(const float* W, int K, int N, int ld, void* WTv, const float* kscale, float wscale, LAS float* scr, int item, int lane_) {
;     ...
;     for (int kk = 0; kk < 64; ++kk) { const float sc = (kscale ? kscale[k0 + kk] : 1.f) * wscale; scr[kk * 65 + lane] = v[kk] * sc; }
.LBB0_180:
	s_waitcnt vmcnt(48)
	v_mul_f32_e32 v22, v55, v61
	s_and_b64 vcc, exec, s[2:3]
	ds_write2_b32 v57, v60, v22 offset0:142 offset1:207
	s_cbranch_vccnz .LBB0_259
	s_waitcnt vmcnt(47)
	v_mul_f32_e32 v22, 0x42800000, v196
	v_mov_b32_e32 v57, v197
	v_pk_mul_f32 v[58:59], v[56:57], v[22:23]
	s_cbranch_execnz .LBB0_183

; template <bool F8> __device__ __forceinline__ void transpose_item(const float* W, int K, int N, int ld, void* WTv, const float* kscale, float wscale, LAS float* scr, int item, int lane_) {
;     ...
;     for (int kk = 0; kk < 64; ++kk) { const float sc = (kscale ? kscale[k0 + kk] : 1.f) * wscale; scr[kk * 65 + lane] = v[kk] * sc; }
.LBB0_183:
	s_waitcnt vmcnt(46)
	v_mul_f32_e32 v22, v53, v59
	v_add_u32_e32 v53, 0x1000, v20
	s_and_b64 vcc, exec, s[2:3]
	ds_write2_b32 v53, v58, v22 offset0:16 offset1:81
	s_cbranch_vccnz .LBB0_260
	s_waitcnt vmcnt(45)
	v_mul_f32_e32 v22, 0x42800000, v198
	v_mov_b32_e32 v55, v199
	v_pk_mul_f32 v[56:57], v[54:55], v[22:23]
	s_cbranch_execnz .LBB0_186

; template <bool F8> __device__ __forceinline__ void transpose_item(const float* W, int K, int N, int ld, void* WTv, const float* kscale, float wscale, LAS float* scr, int item, int lane_) {
;     ...
;     for (int kk = 0; kk < 64; ++kk) { const float sc = (kscale ? kscale[k0 + kk] : 1.f) * wscale; scr[kk * 65 + lane] = v[kk] * sc; }
.LBB0_186:
	s_waitcnt vmcnt(44)
	v_mul_f32_e32 v22, v51, v57
	s_and_b64 vcc, exec, s[2:3]
	ds_write2_b32 v53, v56, v22 offset0:146 offset1:211
	s_cbranch_vccnz .LBB0_261
	s_waitcnt vmcnt(43)
	v_mul_f32_e32 v22, 0x42800000, v200
	v_mov_b32_e32 v53, v201
	v_pk_mul_f32 v[54:55], v[52:53], v[22:23]
	s_cbranch_execnz .LBB0_189

; template <bool F8> __device__ __forceinline__ void transpose_item(const float* W, int K, int N, int ld, void* WTv, const float* kscale, float wscale, LAS float* scr, int item, int lane_) {
;     ...
;     for (int kk = 0; kk < 64; ++kk) { const float sc = (kscale ? kscale[k0 + kk] : 1.f) * wscale; scr[kk * 65 + lane] = v[kk] * sc; }
.LBB0_189:
	s_waitcnt vmcnt(42)
	v_mul_f32_e32 v22, v49, v55
	v_add_u32_e32 v49, 0x1400, v20
	s_and_b64 vcc, exec, s[2:3]
	ds_write2_b32 v49, v54, v22 offset0:20 offset1:85
	s_cbranch_vccnz .LBB0_262
	s_waitcnt vmcnt(41)
	v_mul_f32_e32 v22, 0x42800000, v202
	v_mov_b32_e32 v51, v203
	v_pk_mul_f32 v[52:53], v[50:51], v[22:23]
	s_cbranch_execnz .LBB0_192

; template <bool F8> __device__ __forceinline__ void transpose_item(const float* W, int K, int N, int ld, void* WTv, const float* kscale, float wscale, LAS float* scr, int item, int lane_) {
;     ...
;     for (int kk = 0; kk < 64; ++kk) { const float sc = (kscale ? kscale[k0 + kk] : 1.f) * wscale; scr[kk * 65 + lane] = v[kk] * sc; }
.LBB0_192:
	s_waitcnt vmcnt(40)
	v_mul_f32_e32 v22, v47, v53
	s_and_b64 vcc, exec, s[2:3]
	ds_write2_b32 v49, v52, v22 offset0:150 offset1:215
	s_cbranch_vccnz .LBB0_263
	s_waitcnt vmcnt(39)
	v_mul_f32_e32 v22, 0x42800000, v204
	v_mov_b32_e32 v49, v205
	v_pk_mul_f32 v[50:51], v[48:49], v[22:23]
	s_cbranch_execnz .LBB0_195

; template <bool F8> __device__ __forceinline__ void transpose_item(const float* W, int K, int N, int ld, void* WTv, const float* kscale, float wscale, LAS float* scr, int item, int lane_) {
;     ...
;     for (int kk = 0; kk < 64; ++kk) { const float sc = (kscale ? kscale[k0 + kk] : 1.f) * wscale; scr[kk * 65 + lane] = v[kk] * sc; }
.LBB0_195:
	s_waitcnt vmcnt(38)
	v_mul_f32_e32 v22, v45, v51
	v_add_u32_e32 v45, 0x1800, v20
	s_and_b64 vcc, exec, s[2:3]
	ds_write2_b32 v45, v50, v22 offset0:24 offset1:89
	s_cbranch_vccnz .LBB0_264
	s_waitcnt vmcnt(37)
	v_mul_f32_e32 v22, 0x42800000, v206
	v_mov_b32_e32 v47, v207
	v_pk_mul_f32 v[48:49], v[46:47], v[22:23]
	s_cbranch_execnz .LBB0_198

; template <bool F8> __device__ __forceinline__ void transpose_item(const float* W, int K, int N, int ld, void* WTv, const float* kscale, float wscale, LAS float* scr, int item, int lane_) {
;     ...
;     for (int kk = 0; kk < 64; ++kk) { const float sc = (kscale ? kscale[k0 + kk] : 1.f) * wscale; scr[kk * 65 + lane] = v[kk] * sc; }
.LBB0_198:
	s_waitcnt vmcnt(36)
	v_mul_f32_e32 v22, v43, v49
	s_and_b64 vcc, exec, s[2:3]
	ds_write2_b32 v45, v48, v22 offset0:154 offset1:219
	s_cbranch_vccnz .LBB0_265
	s_waitcnt vmcnt(35)
	v_mul_f32_e32 v22, 0x42800000, v208
	v_mov_b32_e32 v43, v209
	v_pk_mul_f32 v[46:47], v[42:43], v[22:23]
	s_cbranch_execnz .LBB0_201

; template <bool F8> __device__ __forceinline__ void transpose_item(const float* W, int K, int N, int ld, void* WTv, const float* kscale, float wscale, LAS float* scr, int item, int lane_) {
;     ...
;     for (int kk = 0; kk < 64; ++kk) { const float sc = (kscale ? kscale[k0 + kk] : 1.f) * wscale; scr[kk * 65 + lane] = v[kk] * sc; }
.LBB0_201:
	s_waitcnt vmcnt(34)
	v_mul_f32_e32 v22, v39, v47
	v_add_u32_e32 v45, 0x1c00, v20
	s_and_b64 vcc, exec, s[2:3]
	ds_write2_b32 v45, v46, v22 offset0:28 offset1:93
	s_cbranch_vccnz .LBB0_266
	s_waitcnt vmcnt(33)
	v_mul_f32_e32 v22, 0x42800000, v210
	v_mov_b32_e32 v39, v211
	v_pk_mul_f32 v[42:43], v[38:39], v[22:23]
	s_cbranch_execnz .LBB0_204

; template <bool F8> __device__ __forceinline__ void transpose_item(const float* W, int K, int N, int ld, void* WTv, const float* kscale, float wscale, LAS float* scr, int item, int lane_) {
;     ...
;     for (int kk = 0; kk < 64; ++kk) { const float sc = (kscale ? kscale[k0 + kk] : 1.f) * wscale; scr[kk * 65 + lane] = v[kk] * sc; }
.LBB0_204:
	s_waitcnt vmcnt(32)
	v_mul_f32_e32 v22, v37, v43
	s_and_b64 vcc, exec, s[2:3]
	ds_write2_b32 v45, v42, v22 offset0:158 offset1:223
	s_cbranch_vccnz .LBB0_267
	s_waitcnt vmcnt(24)
	v_mul_f32_e32 v22, 0x42800000, v212
	v_mov_b32_e32 v45, v213
	v_pk_mul_f32 v[38:39], v[44:45], v[22:23]
	s_cbranch_execnz .LBB0_207

; template <bool F8> __device__ __forceinline__ void transpose_item(const float* W, int K, int N, int ld, void* WTv, const float* kscale, float wscale, LAS float* scr, int item, int lane_) {
;     ...
;     for (int kk = 0; kk < 64; ++kk) { const float sc = (kscale ? kscale[k0 + kk] : 1.f) * wscale; scr[kk * 65 + lane] = v[kk] * sc; }
.LBB0_207:
	s_waitcnt vmcnt(31)
	v_mul_f32_e32 v22, v41, v39
	v_add_u32_e32 v37, 0x2000, v20
	s_and_b64 vcc, exec, s[2:3]
	ds_write2_b32 v37, v38, v22 offset0:32 offset1:97
	s_cbranch_vccnz .LBB0_268
	s_waitcnt vmcnt(25)
	v_mul_f32_e32 v22, 0x42800000, v214
	v_mov_b32_e32 v41, v215
	v_pk_mul_f32 v[38:39], v[40:41], v[22:23]
	s_cbranch_execnz .LBB0_210

; template <bool F8> __device__ __forceinline__ void transpose_item(const float* W, int K, int N, int ld, void* WTv, const float* kscale, float wscale, LAS float* scr, int item, int lane_) {
;     ...
;     for (int kk = 0; kk < 64; ++kk) { const float sc = (kscale ? kscale[k0 + kk] : 1.f) * wscale; scr[kk * 65 + lane] = v[kk] * sc; }
.LBB0_210:
	s_waitcnt vmcnt(30)
	v_mul_f32_e32 v22, v76, v39
	s_and_b64 vcc, exec, s[2:3]
	ds_write2_b32 v37, v38, v22 offset0:162 offset1:227
	s_cbranch_vccnz .LBB0_269
	s_waitcnt vmcnt(26)
	v_mul_f32_e32 v22, 0x42800000, v216
	v_mov_b32_e32 v37, v217
	v_pk_mul_f32 v[38:39], v[36:37], v[22:23]
	s_cbranch_execnz .LBB0_213

; template <bool F8> __device__ __forceinline__ void transpose_item(const float* W, int K, int N, int ld, void* WTv, const float* kscale, float wscale, LAS float* scr, int item, int lane_) {
;     ...
;     for (int kk = 0; kk < 64; ++kk) { const float sc = (kscale ? kscale[k0 + kk] : 1.f) * wscale; scr[kk * 65 + lane] = v[kk] * sc; }
.LBB0_213:
	s_waitcnt vmcnt(29)
	v_mul_f32_e32 v22, v35, v39
	v_add_u32_e32 v39, 0x2400, v20
	s_and_b64 vcc, exec, s[2:3]
	ds_write2_b32 v39, v38, v22 offset0:36 offset1:101
	s_cbranch_vccnz .LBB0_270
	s_waitcnt vmcnt(26)
	v_mul_f32_e32 v22, 0x42800000, v218
	v_mov_b32_e32 v35, v219
	v_pk_mul_f32 v[36:37], v[34:35], v[22:23]
	s_cbranch_execnz .LBB0_216

; template <bool F8> __device__ __forceinline__ void transpose_item(const float* W, int K, int N, int ld, void* WTv, const float* kscale, float wscale, LAS float* scr, int item, int lane_) {
;     ...
;     for (int kk = 0; kk < 64; ++kk) { const float sc = (kscale ? kscale[k0 + kk] : 1.f) * wscale; scr[kk * 65 + lane] = v[kk] * sc; }
.LBB0_216:
	s_waitcnt vmcnt(28)
	v_mul_f32_e32 v22, v33, v37
	s_and_b64 vcc, exec, s[2:3]
	s_waitcnt vmcnt(26)
	ds_write2_b32 v39, v36, v22 offset0:166 offset1:231
	s_cbranch_vccnz .LBB0_271
	s_waitcnt vmcnt(16)
	v_mul_f32_e32 v22, 0x42800000, v220
	v_mov_b32_e32 v33, v221
	v_pk_mul_f32 v[34:35], v[32:33], v[22:23]
	s_cbranch_execnz .LBB0_219

; template <bool F8> __device__ __forceinline__ void transpose_item(const float* W, int K, int N, int ld, void* WTv, const float* kscale, float wscale, LAS float* scr, int item, int lane_) {
;     ...
;     const int nblk = N / 64, kb = item / nblk, nb = item % nblk, k0 = 64 * kb, n0 = 64 * nb;
;     float v[64];
; #pragma unroll
;     for (int kk = 0; kk < 64; ++kk) v[kk] = W[(size_t)(k0 + kk) * ld + n0 + lane];
; #pragma unroll
;     for (int kk = 0; kk < 64; ++kk) { const float sc = (kscale ? kscale[k0 + kk] : 1.f) * wscale; scr[kk * 65 + lane] = v[kk] * sc; }
.LBB0_287:
	s_ashr_i32 s0, s11, 31
	s_lshr_b32 s0, s0, 27
	s_add_i32 s0, s11, s0
	s_ashr_i32 s0, s0, 5
	s_lshl_b32 s12, s0, 11
	s_lshl_b32 s74, s0, 6
	s_sub_i32 s0, s10, s12
	s_sub_i32 s0, s0, 56
	s_ashr_i32 s1, s0, 31
	s_lshl_b64 s[0:1], s[0:1], 2
	v_mov_b32_e32 v4, v18
	s_add_u32 s0, s8, s0
	s_addc_u32 s1, s9, s1
	v_ashrrev_i32_e32 v5, 31, v4
	v_lshl_add_u64 v[0:1], v[4:5], 2, s[0:1]
	v_mad_i64_i32 v[2:3], s[0:1], s74, v90, v[0:1]
	s_or_b32 s0, s74, 1
	s_nop 0
	v_mad_i64_i32 v[6:7], s[0:1], s0, v90, v[0:1]
	s_or_b32 s0, s74, 2
	s_nop 0
	v_mad_i64_i32 v[8:9], s[0:1], s0, v90, v[0:1]
	s_or_b32 s0, s74, 3
	s_nop 0
	v_mad_i64_i32 v[10:11], s[0:1], s0, v90, v[0:1]
	s_or_b32 s0, s74, 4
	s_nop 0
	v_mad_i64_i32 v[12:13], s[0:1], s0, v90, v[0:1]
	s_or_b32 s0, s74, 5
	s_nop 0
	v_mad_i64_i32 v[14:15], s[0:1], s0, v90, v[0:1]
	s_or_b32 s0, s74, 6
	s_nop 0
	v_mad_i64_i32 v[24:25], s[0:1], s0, v90, v[0:1]
	s_or_b32 s0, s74, 7
	s_nop 0
	v_mad_i64_i32 v[26:27], s[0:1], s0, v90, v[0:1]
	s_or_b32 s0, s74, 8
	s_cmp_lg_u64 s[6:7], 0
	s_cbranch_scc0 .Lks_skip_lbb0_287
	s_lshl_b32 s20, s74, 2
	s_add_u32 s20, s6, s20
	s_addc_u32 s21, s7, 0
	global_load_dwordx4 v[180:183], v21, s[20:21]
	global_load_dwordx4 v[184:187], v21, s[20:21] offset:16
	global_load_dwordx4 v[188:191], v21, s[20:21] offset:32
	global_load_dwordx4 v[192:195], v21, s[20:21] offset:48
	global_load_dwordx4 v[196:199], v21, s[20:21] offset:64
	global_load_dwordx4 v[200:203], v21, s[20:21] offset:80
	global_load_dwordx4 v[204:207], v21, s[20:21] offset:96
	global_load_dwordx4 v[208:211], v21, s[20:21] offset:112
	global_load_dwordx4 v[212:215], v21, s[20:21] offset:128
	global_load_dwordx4 v[216:219], v21, s[20:21] offset:144
	global_load_dwordx4 v[220:223], v21, s[20:21] offset:160
	global_load_dwordx4 v[224:227], v21, s[20:21] offset:176
	global_load_dwordx4 v[228:231], v21, s[20:21] offset:192
	global_load_dwordx4 v[232:235], v21, s[20:21] offset:208
	global_load_dwordx4 v[236:239], v21, s[20:21] offset:224
	global_load_dwordx4 v[240:243], v21, s[20:21] offset:240
.Lks_skip_lbb0_287:
	global_load_dword v73, v[2:3], off
	global_load_dword v75, v[6:7], off
	global_load_dword v74, v[8:9], off
	global_load_dword v72, v[10:11], off
	global_load_dword v69, v[12:13], off
	global_load_dword v71, v[14:15], off
	global_load_dword v70, v[24:25], off
	global_load_dword v68, v[26:27], off
	v_mad_i64_i32 v[2:3], s[0:1], s0, v90, v[0:1]
	s_or_b32 s0, s74, 9
	s_nop 0
	v_mad_i64_i32 v[6:7], s[0:1], s0, v90, v[0:1]
	s_or_b32 s0, s74, 10
	s_nop 0
	v_mad_i64_i32 v[8:9], s[0:1], s0, v90, v[0:1]
	s_or_b32 s0, s74, 11
	s_nop 0
	v_mad_i64_i32 v[10:11], s[0:1], s0, v90, v[0:1]
	s_or_b32 s0, s74, 12
	s_nop 0
	v_mad_i64_i32 v[12:13], s[0:1], s0, v90, v[0:1]
	s_or_b32 s0, s74, 13
	s_nop 0
	v_mad_i64_i32 v[14:15], s[0:1], s0, v90, v[0:1]
	s_or_b32 s0, s74, 14
	s_nop 0
	v_mad_i64_i32 v[24:25], s[0:1], s0, v90, v[0:1]
	s_or_b32 s0, s74, 15
	s_nop 0
	v_mad_i64_i32 v[26:27], s[0:1], s0, v90, v[0:1]
	s_or_b32 s0, s74, 16
	global_load_dword v65, v[2:3], off
	global_load_dword v67, v[6:7], off
	global_load_dword v66, v[8:9], off
	global_load_dword v64, v[10:11], off
	global_load_dword v61, v[12:13], off
	global_load_dword v63, v[14:15], off
	global_load_dword v62, v[24:25], off
	global_load_dword v60, v[26:27], off
	v_mad_i64_i32 v[2:3], s[0:1], s0, v90, v[0:1]
	s_or_b32 s0, s74, 17
	s_nop 0
	v_mad_i64_i32 v[6:7], s[0:1], s0, v90, v[0:1]
	s_or_b32 s0, s74, 18
	s_nop 0
	v_mad_i64_i32 v[8:9], s[0:1], s0, v90, v[0:1]
	s_or_b32 s0, s74, 19
	s_nop 0
	v_mad_i64_i32 v[10:11], s[0:1], s0, v90, v[0:1]
	s_or_b32 s0, s74, 20
	s_nop 0
	v_mad_i64_i32 v[12:13], s[0:1], s0, v90, v[0:1]
	s_or_b32 s0, s74, 21
	s_nop 0
	v_mad_i64_i32 v[14:15], s[0:1], s0, v90, v[0:1]
	s_or_b32 s0, s74, 22
	s_nop 0
	v_mad_i64_i32 v[24:25], s[0:1], s0, v90, v[0:1]
	s_or_b32 s0, s74, 23
	s_nop 0
	v_mad_i64_i32 v[26:27], s[0:1], s0, v90, v[0:1]
	s_or_b32 s0, s74, 24
	global_load_dword v57, v[2:3], off
	global_load_dword v59, v[6:7], off
	global_load_dword v58, v[8:9], off
	global_load_dword v56, v[10:11], off
	global_load_dword v53, v[12:13], off
	global_load_dword v55, v[14:15], off
	global_load_dword v54, v[24:25], off
	global_load_dword v52, v[26:27], off
	v_mad_i64_i32 v[2:3], s[0:1], s0, v90, v[0:1]
	s_or_b32 s0, s74, 25
	s_nop 0
	v_mad_i64_i32 v[6:7], s[0:1], s0, v90, v[0:1]
	s_or_b32 s0, s74, 26
	s_nop 0
	v_mad_i64_i32 v[8:9], s[0:1], s0, v90, v[0:1]
	s_or_b32 s0, s74, 27
	s_nop 0
	v_mad_i64_i32 v[10:11], s[0:1], s0, v90, v[0:1]
	s_or_b32 s0, s74, 28
	s_nop 0
	v_mad_i64_i32 v[12:13], s[0:1], s0, v90, v[0:1]
	s_or_b32 s0, s74, 29
; template <bool F8> __device__ __forceinline__ void transpose_item(const float* W, int K, int N, int ld, void* WTv, const float* kscale, float wscale, LAS float* scr, int item, int lane_) {
;     ...
;     for (int kk = 0; kk < 64; ++kk) v[kk] = W[(size_t)(k0 + kk) * ld + n0 + lane];
; #pragma unroll
;     for (int kk = 0; kk < 64; ++kk) { const float sc = (kscale ? kscale[k0 + kk] : 1.f) * wscale; scr[kk * 65 + lane] = v[kk] * sc; }
	s_nop 0
	v_mad_i64_i32 v[14:15], s[0:1], s0, v90, v[0:1]
	s_or_b32 s0, s74, 30
	s_nop 0
	v_mad_i64_i32 v[24:25], s[0:1], s0, v90, v[0:1]
	s_or_b32 s0, s74, 31
	s_nop 0
	v_mad_i64_i32 v[26:27], s[0:1], s0, v90, v[0:1]
	s_or_b32 s0, s74, 32
	global_load_dword v49, v[2:3], off
	global_load_dword v51, v[6:7], off
	global_load_dword v50, v[8:9], off
	global_load_dword v48, v[10:11], off
	global_load_dword v45, v[12:13], off
	global_load_dword v47, v[14:15], off
	global_load_dword v46, v[24:25], off
	global_load_dword v44, v[26:27], off
	v_mad_i64_i32 v[2:3], s[0:1], s0, v90, v[0:1]
	s_or_b32 s0, s74, 33
	s_nop 0
	v_mad_i64_i32 v[6:7], s[0:1], s0, v90, v[0:1]
	s_or_b32 s0, s74, 34
	s_nop 0
	v_mad_i64_i32 v[8:9], s[0:1], s0, v90, v[0:1]
	s_or_b32 s0, s74, 35
	s_nop 0
	v_mad_i64_i32 v[10:11], s[0:1], s0, v90, v[0:1]
	s_or_b32 s0, s74, 36
	s_nop 0
	v_mad_i64_i32 v[12:13], s[0:1], s0, v90, v[0:1]
	s_or_b32 s0, s74, 37
	s_nop 0
	v_mad_i64_i32 v[14:15], s[0:1], s0, v90, v[0:1]
	s_or_b32 s0, s74, 38
	s_nop 0
	v_mad_i64_i32 v[24:25], s[0:1], s0, v90, v[0:1]
	s_or_b32 s0, s74, 39
	s_nop 0
	v_mad_i64_i32 v[26:27], s[0:1], s0, v90, v[0:1]
	s_or_b32 s0, s74, 40
	global_load_dword v41, v[2:3], off
	global_load_dword v43, v[6:7], off
	global_load_dword v42, v[8:9], off
	global_load_dword v40, v[10:11], off
	global_load_dword v37, v[12:13], off
	global_load_dword v39, v[14:15], off
	global_load_dword v38, v[24:25], off
	global_load_dword v36, v[26:27], off
	v_mad_i64_i32 v[2:3], s[0:1], s0, v90, v[0:1]
	s_or_b32 s0, s74, 41
	s_nop 0
	v_mad_i64_i32 v[6:7], s[0:1], s0, v90, v[0:1]
	s_or_b32 s0, s74, 42
	s_nop 0
	v_mad_i64_i32 v[8:9], s[0:1], s0, v90, v[0:1]
	s_or_b32 s0, s74, 43
	s_nop 0
	v_mad_i64_i32 v[10:11], s[0:1], s0, v90, v[0:1]
	s_or_b32 s0, s74, 44
	s_nop 0
	v_mad_i64_i32 v[12:13], s[0:1], s0, v90, v[0:1]
	s_or_b32 s0, s74, 45
	s_nop 0
	v_mad_i64_i32 v[14:15], s[0:1], s0, v90, v[0:1]
	s_or_b32 s0, s74, 46
	s_nop 0
	v_mad_i64_i32 v[24:25], s[0:1], s0, v90, v[0:1]
	s_or_b32 s0, s74, 47
	s_nop 0
	v_mad_i64_i32 v[26:27], s[0:1], s0, v90, v[0:1]
	s_or_b32 s0, s74, 48
	global_load_dword v33, v[2:3], off
	global_load_dword v35, v[6:7], off
	global_load_dword v34, v[8:9], off
	global_load_dword v32, v[10:11], off
	global_load_dword v29, v[12:13], off
	global_load_dword v31, v[14:15], off
	global_load_dword v30, v[24:25], off
	global_load_dword v28, v[26:27], off
	v_mad_i64_i32 v[2:3], s[0:1], s0, v90, v[0:1]
	s_or_b32 s0, s74, 49
	s_nop 0
	v_mad_i64_i32 v[6:7], s[0:1], s0, v90, v[0:1]
	s_or_b32 s0, s74, 50
	s_nop 0
	v_mad_i64_i32 v[8:9], s[0:1], s0, v90, v[0:1]
	s_or_b32 s0, s74, 51
	s_nop 0
	v_mad_i64_i32 v[10:11], s[0:1], s0, v90, v[0:1]
	s_or_b32 s0, s74, 52
	s_nop 0
	v_mad_i64_i32 v[12:13], s[0:1], s0, v90, v[0:1]
	s_or_b32 s0, s74, 53
	s_nop 0
	v_mad_i64_i32 v[76:77], s[0:1], s0, v90, v[0:1]
	s_or_b32 s0, s74, 54
	s_nop 0
	v_mad_i64_i32 v[78:79], s[0:1], s0, v90, v[0:1]
	s_or_b32 s0, s74, 55
	s_nop 0
	v_mad_i64_i32 v[80:81], s[0:1], s0, v90, v[0:1]
	s_or_b32 s0, s74, 56
	global_load_dword v25, v[2:3], off
	global_load_dword v27, v[6:7], off
	global_load_dword v26, v[8:9], off
	global_load_dword v24, v[10:11], off
	global_load_dword v15, v[12:13], off
	global_load_dword v22, v[76:77], off
	global_load_dword v20, v[78:79], off
	global_load_dword v14, v[80:81], off
	v_mad_i64_i32 v[2:3], s[0:1], s0, v90, v[0:1]
	s_or_b32 s0, s74, 57
	s_nop 0
	v_mad_i64_i32 v[6:7], s[0:1], s0, v90, v[0:1]
	s_or_b32 s0, s74, 58
	s_nop 0
	v_mad_i64_i32 v[8:9], s[0:1], s0, v90, v[0:1]
	s_or_b32 s0, s74, 59
	s_nop 0
	v_mad_i64_i32 v[76:77], s[0:1], s0, v90, v[0:1]
	s_or_b32 s0, s74, 60
	s_nop 0
	v_mad_i64_i32 v[78:79], s[0:1], s0, v90, v[0:1]
	s_or_b32 s0, s74, 61
	s_nop 0
	v_mad_i64_i32 v[80:81], s[0:1], s0, v90, v[0:1]
	s_or_b32 s0, s74, 62
	s_nop 0
	v_mad_i64_i32 v[82:83], s[0:1], s0, v90, v[0:1]
	s_or_b32 s0, s74, 63
	s_nop 0
	v_mad_i64_i32 v[0:1], s[0:1], s0, v90, v[0:1]
	global_load_dword v10, v[2:3], off
	global_load_dword v12, v[6:7], off
	global_load_dword v11, v[8:9], off
	s_nop 0
	global_load_dword v9, v[76:77], off
	global_load_dword v6, v[78:79], off
	global_load_dword v8, v[80:81], off
	global_load_dword v7, v[82:83], off
	global_load_dword v5, v[0:1], off
	s_ashr_i32 s75, s74, 31
	v_cmp_ne_u32_e64 s[4:5], 1, v19
	s_andn2_b64 vcc, exec, s[24:25]
	v_lshl_add_u32 v13, v4, 2, s29
	s_cbranch_vccnz .LBB0_334
	s_waitcnt vmcnt(61)
	v_mul_f32_e32 v76, v73, v180
	v_mul_f32_e32 v1, v75, v181
	v_mul_f32_e32 v0, v74, v182
	v_mov_b32_e32 v2, v182
	v_mov_b32_e32 v3, v183
	ds_write2_b32 v13, v76, v1 offset1:65
	s_cbranch_execnz .LBB0_290

; template <bool F8> __device__ __forceinline__ void transpose_item(const float* W, int K, int N, int ld, void* WTv, const float* kscale, float wscale, LAS float* scr, int item, int lane_) {
;     ...
;     for (int kk = 0; kk < 64; ++kk) { const float sc = (kscale ? kscale[k0 + kk] : 1.f) * wscale; scr[kk * 65 + lane] = v[kk] * sc; }
.LBB0_290:
	s_waitcnt vmcnt(60)
	v_mul_f32_e32 v1, v72, v3
	s_and_b64 vcc, exec, s[4:5]
	v_add_u32_e32 v72, 0x400, v13
	ds_write2_b32 v13, v0, v1 offset0:130 offset1:195
	s_cbranch_vccnz .LBB0_335
	s_waitcnt vmcnt(57)
	v_mul_f32_e32 v73, v69, v184
	v_mul_f32_e32 v1, v71, v185
	v_mul_f32_e32 v0, v70, v186
	v_mov_b32_e32 v2, v186
	v_mov_b32_e32 v3, v187
	ds_write2_b32 v72, v73, v1 offset0:4 offset1:69
	s_cbranch_execnz .LBB0_293

; template <bool F8> __device__ __forceinline__ void transpose_item(const float* W, int K, int N, int ld, void* WTv, const float* kscale, float wscale, LAS float* scr, int item, int lane_) {
;     ...
;     for (int kk = 0; kk < 64; ++kk) { const float sc = (kscale ? kscale[k0 + kk] : 1.f) * wscale; scr[kk * 65 + lane] = v[kk] * sc; }
.LBB0_293:
	s_waitcnt vmcnt(56)
	v_mul_f32_e32 v1, v68, v3
	s_and_b64 vcc, exec, s[4:5]
	v_add_u32_e32 v68, 0x800, v13
	ds_write2_b32 v72, v0, v1 offset0:134 offset1:199
	s_cbranch_vccnz .LBB0_336
	s_waitcnt vmcnt(53)
	v_mul_f32_e32 v69, v65, v188
	v_mul_f32_e32 v1, v67, v189
	v_mul_f32_e32 v0, v66, v190
	v_mov_b32_e32 v2, v190
	v_mov_b32_e32 v3, v191
	ds_write2_b32 v68, v69, v1 offset0:8 offset1:73
	s_cbranch_execnz .LBB0_296

; template <bool F8> __device__ __forceinline__ void transpose_item(const float* W, int K, int N, int ld, void* WTv, const float* kscale, float wscale, LAS float* scr, int item, int lane_) {
;     ...
;     for (int kk = 0; kk < 64; ++kk) { const float sc = (kscale ? kscale[k0 + kk] : 1.f) * wscale; scr[kk * 65 + lane] = v[kk] * sc; }
.LBB0_296:
	s_waitcnt vmcnt(52)
	v_mul_f32_e32 v1, v64, v3
	s_and_b64 vcc, exec, s[4:5]
	v_add_u32_e32 v64, 0xc00, v13
	ds_write2_b32 v68, v0, v1 offset0:138 offset1:203
	s_cbranch_vccnz .LBB0_337
	s_waitcnt vmcnt(49)
	v_mul_f32_e32 v65, v61, v192
	v_mul_f32_e32 v1, v63, v193
	v_mul_f32_e32 v0, v62, v194
	v_mov_b32_e32 v2, v194
	v_mov_b32_e32 v3, v195
	ds_write2_b32 v64, v65, v1 offset0:12 offset1:77
	s_cbranch_execnz .LBB0_299

; template <bool F8> __device__ __forceinline__ void transpose_item(const float* W, int K, int N, int ld, void* WTv, const float* kscale, float wscale, LAS float* scr, int item, int lane_) {
;     ...
;     for (int kk = 0; kk < 64; ++kk) { const float sc = (kscale ? kscale[k0 + kk] : 1.f) * wscale; scr[kk * 65 + lane] = v[kk] * sc; }
.LBB0_299:
	s_waitcnt vmcnt(48)
	v_mul_f32_e32 v1, v60, v3
	s_and_b64 vcc, exec, s[4:5]
	v_add_u32_e32 v60, 0x1000, v13
	ds_write2_b32 v64, v0, v1 offset0:142 offset1:207
	s_cbranch_vccnz .LBB0_338
	s_waitcnt vmcnt(45)
	v_mul_f32_e32 v61, v57, v196
	v_mul_f32_e32 v1, v59, v197
	v_mul_f32_e32 v0, v58, v198
	v_mov_b32_e32 v2, v198
	v_mov_b32_e32 v3, v199
	ds_write2_b32 v60, v61, v1 offset0:16 offset1:81
	s_cbranch_execnz .LBB0_302

; template <bool F8> __device__ __forceinline__ void transpose_item(const float* W, int K, int N, int ld, void* WTv, const float* kscale, float wscale, LAS float* scr, int item, int lane_) {
;     ...
;     for (int kk = 0; kk < 64; ++kk) { const float sc = (kscale ? kscale[k0 + kk] : 1.f) * wscale; scr[kk * 65 + lane] = v[kk] * sc; }
.LBB0_302:
	s_waitcnt vmcnt(44)
	v_mul_f32_e32 v1, v56, v3
	s_and_b64 vcc, exec, s[4:5]
	v_add_u32_e32 v56, 0x1400, v13
	ds_write2_b32 v60, v0, v1 offset0:146 offset1:211
	s_cbranch_vccnz .LBB0_339
	s_waitcnt vmcnt(41)
	v_mul_f32_e32 v57, v53, v200
	v_mul_f32_e32 v1, v55, v201
	v_mul_f32_e32 v0, v54, v202
	v_mov_b32_e32 v2, v202
	v_mov_b32_e32 v3, v203
	ds_write2_b32 v56, v57, v1 offset0:20 offset1:85
	s_cbranch_execnz .LBB0_305

; template <bool F8> __device__ __forceinline__ void transpose_item(const float* W, int K, int N, int ld, void* WTv, const float* kscale, float wscale, LAS float* scr, int item, int lane_) {
;     ...
;     for (int kk = 0; kk < 64; ++kk) { const float sc = (kscale ? kscale[k0 + kk] : 1.f) * wscale; scr[kk * 65 + lane] = v[kk] * sc; }
.LBB0_305:
	s_waitcnt vmcnt(40)
	v_mul_f32_e32 v1, v52, v3
	s_and_b64 vcc, exec, s[4:5]
	v_add_u32_e32 v52, 0x1800, v13
	ds_write2_b32 v56, v0, v1 offset0:150 offset1:215
	s_cbranch_vccnz .LBB0_340
	s_waitcnt vmcnt(37)
	v_mul_f32_e32 v53, v49, v204
	v_mul_f32_e32 v1, v51, v205
	v_mul_f32_e32 v0, v50, v206
	v_mov_b32_e32 v2, v206
	v_mov_b32_e32 v3, v207
	ds_write2_b32 v52, v53, v1 offset0:24 offset1:89
	s_cbranch_execnz .LBB0_308

; template <bool F8> __device__ __forceinline__ void transpose_item(const float* W, int K, int N, int ld, void* WTv, const float* kscale, float wscale, LAS float* scr, int item, int lane_) {
;     ...
;     for (int kk = 0; kk < 64; ++kk) v[kk] = W[(size_t)(k0 + kk) * ld + n0 + lane];
; #pragma unroll
;     for (int kk = 0; kk < 64; ++kk) { const float sc = (kscale ? kscale[k0 + kk] : 1.f) * wscale; scr[kk * 65 + lane] = v[kk] * sc; }
.LBB0_308:
	s_waitcnt vmcnt(36)
	v_mul_f32_e32 v1, v48, v3
	s_and_b64 vcc, exec, s[4:5]
	v_add_u32_e32 v48, 0x1c00, v13
	ds_write2_b32 v52, v0, v1 offset0:154 offset1:219
	s_cbranch_vccnz .LBB0_341
	s_waitcnt vmcnt(33)
	v_mul_f32_e32 v49, v45, v208
	v_mul_f32_e32 v1, v47, v209
	v_mul_f32_e32 v0, v46, v210
	v_mov_b32_e32 v2, v210
	v_mov_b32_e32 v3, v211
	ds_write2_b32 v48, v49, v1 offset0:28 offset1:93
	s_cbranch_execnz .LBB0_311

; template <bool F8> __device__ __forceinline__ void transpose_item(const float* W, int K, int N, int ld, void* WTv, const float* kscale, float wscale, LAS float* scr, int item, int lane_) {
;     ...
;     for (int kk = 0; kk < 64; ++kk) v[kk] = W[(size_t)(k0 + kk) * ld + n0 + lane];
; #pragma unroll
;     for (int kk = 0; kk < 64; ++kk) { const float sc = (kscale ? kscale[k0 + kk] : 1.f) * wscale; scr[kk * 65 + lane] = v[kk] * sc; }
.LBB0_311:
	s_waitcnt vmcnt(32)
	v_mul_f32_e32 v1, v44, v3
	s_and_b64 vcc, exec, s[4:5]
	v_add_u32_e32 v44, 0x2000, v13
	ds_write2_b32 v48, v0, v1 offset0:158 offset1:223
	s_cbranch_vccnz .LBB0_342
	s_waitcnt vmcnt(29)
	v_mul_f32_e32 v45, v41, v212
	v_mul_f32_e32 v1, v43, v213
	v_mul_f32_e32 v0, v42, v214
	v_mov_b32_e32 v2, v214
	v_mov_b32_e32 v3, v215
	ds_write2_b32 v44, v45, v1 offset0:32 offset1:97
	s_cbranch_execnz .LBB0_314

; template <bool F8> __device__ __forceinline__ void transpose_item(const float* W, int K, int N, int ld, void* WTv, const float* kscale, float wscale, LAS float* scr, int item, int lane_) {
;     ...
;     for (int kk = 0; kk < 64; ++kk) v[kk] = W[(size_t)(k0 + kk) * ld + n0 + lane];
; #pragma unroll
;     for (int kk = 0; kk < 64; ++kk) { const float sc = (kscale ? kscale[k0 + kk] : 1.f) * wscale; scr[kk * 65 + lane] = v[kk] * sc; }
.LBB0_314:
	s_waitcnt vmcnt(28)
	v_mul_f32_e32 v1, v40, v3
	s_and_b64 vcc, exec, s[4:5]
	v_add_u32_e32 v40, 0x2400, v13
	ds_write2_b32 v44, v0, v1 offset0:162 offset1:227
	s_cbranch_vccnz .LBB0_343
	s_waitcnt vmcnt(25)
	v_mul_f32_e32 v41, v37, v216
	v_mul_f32_e32 v1, v39, v217
	v_mul_f32_e32 v0, v38, v218
	v_mov_b32_e32 v2, v218
	v_mov_b32_e32 v3, v219
	ds_write2_b32 v40, v41, v1 offset0:36 offset1:101
	s_cbranch_execnz .LBB0_317

; template <bool F8> __device__ __forceinline__ void transpose_item(const float* W, int K, int N, int ld, void* WTv, const float* kscale, float wscale, LAS float* scr, int item, int lane_) {
;     ...
;     for (int kk = 0; kk < 64; ++kk) v[kk] = W[(size_t)(k0 + kk) * ld + n0 + lane];
; #pragma unroll
;     for (int kk = 0; kk < 64; ++kk) { const float sc = (kscale ? kscale[k0 + kk] : 1.f) * wscale; scr[kk * 65 + lane] = v[kk] * sc; }
.LBB0_317:
	s_waitcnt vmcnt(24)
	v_mul_f32_e32 v1, v36, v3
	s_and_b64 vcc, exec, s[4:5]
	v_add_u32_e32 v36, 0x2800, v13
	ds_write2_b32 v40, v0, v1 offset0:166 offset1:231
	s_cbranch_vccnz .LBB0_344
	s_waitcnt vmcnt(21)
	v_mul_f32_e32 v37, v33, v220
	v_mul_f32_e32 v1, v35, v221
	v_mul_f32_e32 v0, v34, v222
	v_mov_b32_e32 v2, v222
	v_mov_b32_e32 v3, v223
	ds_write2_b32 v36, v37, v1 offset0:40 offset1:105
	s_cbranch_execnz .LBB0_320

; template <bool F8> __device__ __forceinline__ void transpose_item(const float* W, int K, int N, int ld, void* WTv, const float* kscale, float wscale, LAS float* scr, int item, int lane_) {
;     ...
;     for (int kk = 0; kk < 64; ++kk) v[kk] = W[(size_t)(k0 + kk) * ld + n0 + lane];
; #pragma unroll
;     for (int kk = 0; kk < 64; ++kk) { const float sc = (kscale ? kscale[k0 + kk] : 1.f) * wscale; scr[kk * 65 + lane] = v[kk] * sc; }
.LBB0_320:
	s_waitcnt vmcnt(20)
	v_mul_f32_e32 v1, v32, v3
	s_and_b64 vcc, exec, s[4:5]
	v_add_u32_e32 v32, 0x2c00, v13
	ds_write2_b32 v36, v0, v1 offset0:170 offset1:235
	s_cbranch_vccnz .LBB0_345
	s_waitcnt vmcnt(17)
	v_mul_f32_e32 v33, v29, v224
	v_mul_f32_e32 v1, v31, v225
	v_mul_f32_e32 v0, v30, v226
	v_mov_b32_e32 v2, v226
	v_mov_b32_e32 v3, v227
	ds_write2_b32 v32, v33, v1 offset0:44 offset1:109
	s_cbranch_execnz .LBB0_323

; template <bool F8> __device__ __forceinline__ void transpose_item(const float* W, int K, int N, int ld, void* WTv, const float* kscale, float wscale, LAS float* scr, int item, int lane_) {
;     ...
;     for (int kk = 0; kk < 64; ++kk) v[kk] = W[(size_t)(k0 + kk) * ld + n0 + lane];
; #pragma unroll
;     for (int kk = 0; kk < 64; ++kk) { const float sc = (kscale ? kscale[k0 + kk] : 1.f) * wscale; scr[kk * 65 + lane] = v[kk] * sc; }
.LBB0_323:
	s_waitcnt vmcnt(16)
	v_mul_f32_e32 v1, v28, v3
	s_and_b64 vcc, exec, s[4:5]
	v_add_u32_e32 v28, 0x3000, v13
	ds_write2_b32 v32, v0, v1 offset0:174 offset1:239
	s_cbranch_vccnz .LBB0_346
	s_waitcnt vmcnt(13)
	v_mul_f32_e32 v29, v25, v228
	v_mul_f32_e32 v1, v27, v229
	v_mul_f32_e32 v0, v26, v230
	v_mov_b32_e32 v2, v230
	v_mov_b32_e32 v3, v231
	ds_write2_b32 v28, v29, v1 offset0:48 offset1:113
	s_cbranch_execnz .LBB0_326

; template <bool F8> __device__ __forceinline__ void transpose_item(const float* W, int K, int N, int ld, void* WTv, const float* kscale, float wscale, LAS float* scr, int item, int lane_) {
;     ...
;     for (int kk = 0; kk < 64; ++kk) v[kk] = W[(size_t)(k0 + kk) * ld + n0 + lane];
; #pragma unroll
;     for (int kk = 0; kk < 64; ++kk) { const float sc = (kscale ? kscale[k0 + kk] : 1.f) * wscale; scr[kk * 65 + lane] = v[kk] * sc; }
.LBB0_326:
	s_waitcnt vmcnt(12)
	v_mul_f32_e32 v1, v24, v3
	s_and_b64 vcc, exec, s[4:5]
	v_add_u32_e32 v24, 0x3400, v13
	ds_write2_b32 v28, v0, v1 offset0:178 offset1:243
	s_cbranch_vccnz .LBB0_347
	s_waitcnt vmcnt(9)
	v_mul_f32_e32 v25, v15, v232
	v_mul_f32_e32 v1, v22, v233
	v_mul_f32_e32 v0, v20, v234
	v_mov_b32_e32 v2, v234
	v_mov_b32_e32 v3, v235
	ds_write2_b32 v24, v25, v1 offset0:52 offset1:117
	s_cbranch_execnz .LBB0_329

; template <bool F8> __device__ __forceinline__ void transpose_item(const float* W, int K, int N, int ld, void* WTv, const float* kscale, float wscale, LAS float* scr, int item, int lane_) {
;     ...
;     for (int kk = 0; kk < 64; ++kk) v[kk] = W[(size_t)(k0 + kk) * ld + n0 + lane];
; #pragma unroll
;     for (int kk = 0; kk < 64; ++kk) { const float sc = (kscale ? kscale[k0 + kk] : 1.f) * wscale; scr[kk * 65 + lane] = v[kk] * sc; }
.LBB0_329:
	s_waitcnt vmcnt(8)
	v_mul_f32_e32 v1, v14, v3
	s_and_b64 vcc, exec, s[4:5]
	v_add_u32_e32 v14, 0x3800, v13
	ds_write2_b32 v24, v0, v1 offset0:182 offset1:247
	s_cbranch_vccnz .LBB0_348
	s_waitcnt vmcnt(5)
	v_mul_f32_e32 v15, v10, v236
	v_mul_f32_e32 v1, v12, v237
	v_mul_f32_e32 v0, v11, v238
	v_mov_b32_e32 v2, v238
	v_mov_b32_e32 v3, v239
	ds_write2_b32 v14, v15, v1 offset0:56 offset1:121
	s_cbranch_execnz .LBB0_332

; template <bool F8> __device__ __forceinline__ void transpose_item(const float* W, int K, int N, int ld, void* WTv, const float* kscale, float wscale, LAS float* scr, int item, int lane_) {
;     ...
;     for (int kk = 0; kk < 64; ++kk) v[kk] = W[(size_t)(k0 + kk) * ld + n0 + lane];
; #pragma unroll
;     for (int kk = 0; kk < 64; ++kk) { const float sc = (kscale ? kscale[k0 + kk] : 1.f) * wscale; scr[kk * 65 + lane] = v[kk] * sc; }
.LBB0_332:
	s_waitcnt vmcnt(4)
	v_mul_f32_e32 v1, v9, v3
	s_and_b64 vcc, exec, s[4:5]
	v_add_u32_e32 v9, 0x3c00, v13
	ds_write2_b32 v14, v0, v1 offset0:186 offset1:251
	s_cbranch_vccnz .LBB0_349
	s_waitcnt vmcnt(1)
	v_mul_f32_e32 v10, v6, v240
	v_mul_f32_e32 v1, v8, v241
	v_mul_f32_e32 v0, v7, v242
	v_mov_b32_e32 v2, v242
	v_mov_b32_e32 v3, v243
	ds_write2_b32 v9, v10, v1 offset0:60 offset1:125
	s_cbranch_execnz .LBB0_286
	s_branch .LBB0_350

; template <bool F8> __device__ __forceinline__ void transpose_item(const float* W, int K, int N, int ld, void* WTv, const float* kscale, float wscale, LAS float* scr, int item, int lane_) {
;     ...
;     const int nblk = N / 64, kb = item / nblk, nb = item % nblk, k0 = 64 * kb, n0 = 64 * nb;
;     float v[64];
; #pragma unroll
;     for (int kk = 0; kk < 64; ++kk) v[kk] = W[(size_t)(k0 + kk) * ld + n0 + lane];
; #pragma unroll
;     for (int kk = 0; kk < 64; ++kk) { const float sc = (kscale ? kscale[k0 + kk] : 1.f) * wscale; scr[kk * 65 + lane] = v[kk] * sc; }
.LBB0_433:
	s_ashr_i32 s0, s13, 31
	s_lshr_b32 s0, s0, 27
	s_add_i32 s0, s13, s0
	s_ashr_i32 s0, s0, 5
	s_lshl_b32 s14, s0, 11
	s_lshl_b32 s4, s0, 6
	s_sub_i32 s0, s12, s14
	s_sub_i32 s0, s0, 56
	s_ashr_i32 s1, s0, 31
	s_lshl_b64 s[0:1], s[0:1], 2
	v_mov_b32_e32 v4, v18
	s_add_u32 s0, s6, s0
	s_addc_u32 s1, s7, s1
	v_ashrrev_i32_e32 v5, 31, v4
	s_ashr_i32 s5, s4, 31
	v_lshl_add_u64 v[0:1], v[4:5], 2, s[0:1]
	s_lshl_b64 s[0:1], s[4:5], 13
	v_lshl_add_u64 v[2:3], v[0:1], 0, s[0:1]
	s_or_b32 s0, s4, 1
	s_ashr_i32 s1, s0, 31
	s_lshl_b64 s[0:1], s[0:1], 13
	v_lshl_add_u64 v[6:7], v[0:1], 0, s[0:1]
	s_or_b32 s0, s4, 2
	s_ashr_i32 s1, s0, 31
	s_lshl_b64 s[0:1], s[0:1], 13
	v_lshl_add_u64 v[8:9], v[0:1], 0, s[0:1]
	s_or_b32 s0, s4, 3
	s_ashr_i32 s1, s0, 31
	s_lshl_b64 s[0:1], s[0:1], 13
	v_lshl_add_u64 v[10:11], v[0:1], 0, s[0:1]
	s_or_b32 s0, s4, 4
	s_ashr_i32 s1, s0, 31
	s_lshl_b64 s[0:1], s[0:1], 13
	v_lshl_add_u64 v[12:13], v[0:1], 0, s[0:1]
	s_or_b32 s0, s4, 5
	s_ashr_i32 s1, s0, 31
	s_lshl_b64 s[0:1], s[0:1], 13
	v_lshl_add_u64 v[14:15], v[0:1], 0, s[0:1]
	s_or_b32 s0, s4, 6
	s_ashr_i32 s1, s0, 31
	s_lshl_b64 s[0:1], s[0:1], 13
	v_lshl_add_u64 v[24:25], v[0:1], 0, s[0:1]
	s_or_b32 s0, s4, 7
	s_ashr_i32 s1, s0, 31
	s_lshl_b64 s[0:1], s[0:1], 13
	v_lshl_add_u64 v[26:27], v[0:1], 0, s[0:1]
	s_or_b32 s0, s4, 8
	s_ashr_i32 s1, s0, 31
	s_lshl_b64 s[0:1], s[0:1], 13
	s_cmp_lg_u64 s[10:11], 0
	s_cbranch_scc0 .Lks_skip_lbb0_433
	s_lshl_b32 s20, s4, 2
	s_add_u32 s20, s10, s20
	s_addc_u32 s21, s11, 0
	global_load_dwordx4 v[180:183], v21, s[20:21]
	global_load_dwordx4 v[184:187], v21, s[20:21] offset:16
	global_load_dwordx4 v[188:191], v21, s[20:21] offset:32
	global_load_dwordx4 v[192:195], v21, s[20:21] offset:48
	global_load_dwordx4 v[196:199], v21, s[20:21] offset:64
	global_load_dwordx4 v[200:203], v21, s[20:21] offset:80
	global_load_dwordx4 v[204:207], v21, s[20:21] offset:96
	global_load_dwordx4 v[208:211], v21, s[20:21] offset:112
	global_load_dwordx4 v[212:215], v21, s[20:21] offset:128
	global_load_dwordx4 v[216:219], v21, s[20:21] offset:144
	global_load_dwordx4 v[220:223], v21, s[20:21] offset:160
	global_load_dwordx4 v[224:227], v21, s[20:21] offset:176
	global_load_dwordx4 v[228:231], v21, s[20:21] offset:192
	global_load_dwordx4 v[232:235], v21, s[20:21] offset:208
	global_load_dwordx4 v[236:239], v21, s[20:21] offset:224
	global_load_dwordx4 v[240:243], v21, s[20:21] offset:240
.Lks_skip_lbb0_433:
	global_load_dword v73, v[2:3], off
	global_load_dword v75, v[6:7], off
	global_load_dword v74, v[8:9], off
	global_load_dword v72, v[10:11], off
	global_load_dword v65, v[12:13], off
	global_load_dword v67, v[14:15], off
	global_load_dword v66, v[24:25], off
	global_load_dword v64, v[26:27], off
	v_lshl_add_u64 v[2:3], v[0:1], 0, s[0:1]
	s_or_b32 s0, s4, 9
	s_ashr_i32 s1, s0, 31
	s_lshl_b64 s[0:1], s[0:1], 13
	v_lshl_add_u64 v[6:7], v[0:1], 0, s[0:1]
	s_or_b32 s0, s4, 10
	s_ashr_i32 s1, s0, 31
	s_lshl_b64 s[0:1], s[0:1], 13
	v_lshl_add_u64 v[8:9], v[0:1], 0, s[0:1]
	s_or_b32 s0, s4, 11
	s_ashr_i32 s1, s0, 31
	s_lshl_b64 s[0:1], s[0:1], 13
	v_lshl_add_u64 v[10:11], v[0:1], 0, s[0:1]
	s_or_b32 s0, s4, 12
	s_ashr_i32 s1, s0, 31
	s_lshl_b64 s[0:1], s[0:1], 13
	v_lshl_add_u64 v[12:13], v[0:1], 0, s[0:1]
	s_or_b32 s0, s4, 13
	s_ashr_i32 s1, s0, 31
	s_lshl_b64 s[0:1], s[0:1], 13
	v_lshl_add_u64 v[14:15], v[0:1], 0, s[0:1]
	s_or_b32 s0, s4, 14
	s_ashr_i32 s1, s0, 31
	s_lshl_b64 s[0:1], s[0:1], 13
	v_lshl_add_u64 v[24:25], v[0:1], 0, s[0:1]
	s_or_b32 s0, s4, 15
	s_ashr_i32 s1, s0, 31
	s_lshl_b64 s[0:1], s[0:1], 13
	v_lshl_add_u64 v[26:27], v[0:1], 0, s[0:1]
	s_or_b32 s0, s4, 16
	s_ashr_i32 s1, s0, 31
	s_lshl_b64 s[0:1], s[0:1], 13
	global_load_dword v69, v[2:3], off
	global_load_dword v71, v[6:7], off
	global_load_dword v70, v[8:9], off
	global_load_dword v68, v[10:11], off
	global_load_dword v57, v[12:13], off
	global_load_dword v59, v[14:15], off
	global_load_dword v58, v[24:25], off
	global_load_dword v56, v[26:27], off
	v_lshl_add_u64 v[2:3], v[0:1], 0, s[0:1]
	s_or_b32 s0, s4, 17
	s_ashr_i32 s1, s0, 31
	s_lshl_b64 s[0:1], s[0:1], 13
	v_lshl_add_u64 v[6:7], v[0:1], 0, s[0:1]
	s_or_b32 s0, s4, 18
	s_ashr_i32 s1, s0, 31
	s_lshl_b64 s[0:1], s[0:1], 13
	v_lshl_add_u64 v[8:9], v[0:1], 0, s[0:1]
	s_or_b32 s0, s4, 19
	s_ashr_i32 s1, s0, 31
	s_lshl_b64 s[0:1], s[0:1], 13
	v_lshl_add_u64 v[10:11], v[0:1], 0, s[0:1]
	s_or_b32 s0, s4, 20
	s_ashr_i32 s1, s0, 31
	s_lshl_b64 s[0:1], s[0:1], 13
	v_lshl_add_u64 v[12:13], v[0:1], 0, s[0:1]
	s_or_b32 s0, s4, 21
	s_ashr_i32 s1, s0, 31
	s_lshl_b64 s[0:1], s[0:1], 13
	v_lshl_add_u64 v[14:15], v[0:1], 0, s[0:1]
	s_or_b32 s0, s4, 22
	s_ashr_i32 s1, s0, 31
	s_lshl_b64 s[0:1], s[0:1], 13
	v_lshl_add_u64 v[24:25], v[0:1], 0, s[0:1]
	s_or_b32 s0, s4, 23
	s_ashr_i32 s1, s0, 31
	s_lshl_b64 s[0:1], s[0:1], 13
	v_lshl_add_u64 v[26:27], v[0:1], 0, s[0:1]
	s_or_b32 s0, s4, 24
	s_ashr_i32 s1, s0, 31
	s_lshl_b64 s[0:1], s[0:1], 13
	global_load_dword v61, v[2:3], off
	global_load_dword v63, v[6:7], off
	global_load_dword v62, v[8:9], off
	global_load_dword v60, v[10:11], off
	global_load_dword v49, v[12:13], off
	global_load_dword v51, v[14:15], off
	global_load_dword v50, v[24:25], off
	global_load_dword v48, v[26:27], off
	v_lshl_add_u64 v[2:3], v[0:1], 0, s[0:1]
	s_or_b32 s0, s4, 25
	s_ashr_i32 s1, s0, 31
	s_lshl_b64 s[0:1], s[0:1], 13
	v_lshl_add_u64 v[6:7], v[0:1], 0, s[0:1]
	s_or_b32 s0, s4, 26
	s_ashr_i32 s1, s0, 31
	s_lshl_b64 s[0:1], s[0:1], 13
	v_lshl_add_u64 v[8:9], v[0:1], 0, s[0:1]
	s_or_b32 s0, s4, 27
	s_ashr_i32 s1, s0, 31
	s_lshl_b64 s[0:1], s[0:1], 13
	v_lshl_add_u64 v[10:11], v[0:1], 0, s[0:1]
	s_or_b32 s0, s4, 28
; template <bool F8> __device__ __forceinline__ void transpose_item(const float* W, int K, int N, int ld, void* WTv, const float* kscale, float wscale, LAS float* scr, int item, int lane_) {
;     ...
;     for (int kk = 0; kk < 64; ++kk) v[kk] = W[(size_t)(k0 + kk) * ld + n0 + lane];
; #pragma unroll
;     for (int kk = 0; kk < 64; ++kk) { const float sc = (kscale ? kscale[k0 + kk] : 1.f) * wscale; scr[kk * 65 + lane] = v[kk] * sc; }
	s_ashr_i32 s1, s0, 31
	s_lshl_b64 s[0:1], s[0:1], 13
	v_lshl_add_u64 v[12:13], v[0:1], 0, s[0:1]
	s_or_b32 s0, s4, 29
	s_ashr_i32 s1, s0, 31
	s_lshl_b64 s[0:1], s[0:1], 13
	v_lshl_add_u64 v[14:15], v[0:1], 0, s[0:1]
	s_or_b32 s0, s4, 30
	s_ashr_i32 s1, s0, 31
	s_lshl_b64 s[0:1], s[0:1], 13
	v_lshl_add_u64 v[24:25], v[0:1], 0, s[0:1]
	s_or_b32 s0, s4, 31
	s_ashr_i32 s1, s0, 31
	s_lshl_b64 s[0:1], s[0:1], 13
	v_lshl_add_u64 v[26:27], v[0:1], 0, s[0:1]
	s_or_b32 s0, s4, 32
	s_ashr_i32 s1, s0, 31
	s_lshl_b64 s[0:1], s[0:1], 13
	global_load_dword v53, v[2:3], off
	global_load_dword v55, v[6:7], off
	global_load_dword v54, v[8:9], off
	global_load_dword v52, v[10:11], off
	global_load_dword v41, v[12:13], off
	global_load_dword v43, v[14:15], off
	global_load_dword v42, v[24:25], off
	global_load_dword v40, v[26:27], off
	v_lshl_add_u64 v[2:3], v[0:1], 0, s[0:1]
	s_or_b32 s0, s4, 33
	s_ashr_i32 s1, s0, 31
	s_lshl_b64 s[0:1], s[0:1], 13
	v_lshl_add_u64 v[6:7], v[0:1], 0, s[0:1]
	s_or_b32 s0, s4, 34
	s_ashr_i32 s1, s0, 31
	s_lshl_b64 s[0:1], s[0:1], 13
	v_lshl_add_u64 v[8:9], v[0:1], 0, s[0:1]
	s_or_b32 s0, s4, 35
	s_ashr_i32 s1, s0, 31
	s_lshl_b64 s[0:1], s[0:1], 13
	v_lshl_add_u64 v[10:11], v[0:1], 0, s[0:1]
	s_or_b32 s0, s4, 36
	s_ashr_i32 s1, s0, 31
	s_lshl_b64 s[0:1], s[0:1], 13
	v_lshl_add_u64 v[12:13], v[0:1], 0, s[0:1]
	s_or_b32 s0, s4, 37
	s_ashr_i32 s1, s0, 31
	s_lshl_b64 s[0:1], s[0:1], 13
	v_lshl_add_u64 v[14:15], v[0:1], 0, s[0:1]
	s_or_b32 s0, s4, 38
	s_ashr_i32 s1, s0, 31
	s_lshl_b64 s[0:1], s[0:1], 13
	v_lshl_add_u64 v[24:25], v[0:1], 0, s[0:1]
	s_or_b32 s0, s4, 39
	s_ashr_i32 s1, s0, 31
	s_lshl_b64 s[0:1], s[0:1], 13
	v_lshl_add_u64 v[26:27], v[0:1], 0, s[0:1]
	s_or_b32 s0, s4, 40
	s_ashr_i32 s1, s0, 31
	s_lshl_b64 s[0:1], s[0:1], 13
	global_load_dword v45, v[2:3], off
	global_load_dword v47, v[6:7], off
	global_load_dword v46, v[8:9], off
	global_load_dword v44, v[10:11], off
	global_load_dword v33, v[12:13], off
	global_load_dword v35, v[14:15], off
	global_load_dword v34, v[24:25], off
	global_load_dword v32, v[26:27], off
	v_lshl_add_u64 v[2:3], v[0:1], 0, s[0:1]
	s_or_b32 s0, s4, 41
	s_ashr_i32 s1, s0, 31
	s_lshl_b64 s[0:1], s[0:1], 13
	v_lshl_add_u64 v[6:7], v[0:1], 0, s[0:1]
	s_or_b32 s0, s4, 42
	s_ashr_i32 s1, s0, 31
	s_lshl_b64 s[0:1], s[0:1], 13
	v_lshl_add_u64 v[8:9], v[0:1], 0, s[0:1]
	s_or_b32 s0, s4, 43
	s_ashr_i32 s1, s0, 31
	s_lshl_b64 s[0:1], s[0:1], 13
	v_lshl_add_u64 v[10:11], v[0:1], 0, s[0:1]
	s_or_b32 s0, s4, 44
	s_ashr_i32 s1, s0, 31
	s_lshl_b64 s[0:1], s[0:1], 13
	v_lshl_add_u64 v[12:13], v[0:1], 0, s[0:1]
	s_or_b32 s0, s4, 45
	s_ashr_i32 s1, s0, 31
	s_lshl_b64 s[0:1], s[0:1], 13
	v_lshl_add_u64 v[14:15], v[0:1], 0, s[0:1]
	s_or_b32 s0, s4, 46
	s_ashr_i32 s1, s0, 31
	s_lshl_b64 s[0:1], s[0:1], 13
	v_lshl_add_u64 v[28:29], v[0:1], 0, s[0:1]
	s_or_b32 s0, s4, 47
	s_ashr_i32 s1, s0, 31
	s_lshl_b64 s[0:1], s[0:1], 13
	v_lshl_add_u64 v[30:31], v[0:1], 0, s[0:1]
	s_or_b32 s0, s4, 48
	s_ashr_i32 s1, s0, 31
	s_lshl_b64 s[0:1], s[0:1], 13
	global_load_dword v37, v[2:3], off
	global_load_dword v39, v[6:7], off
	global_load_dword v38, v[8:9], off
	global_load_dword v36, v[10:11], off
	global_load_dword v25, v[12:13], off
	global_load_dword v27, v[14:15], off
	global_load_dword v26, v[28:29], off
	global_load_dword v24, v[30:31], off
	v_lshl_add_u64 v[2:3], v[0:1], 0, s[0:1]
	s_or_b32 s0, s4, 49
	s_ashr_i32 s1, s0, 31
	s_lshl_b64 s[0:1], s[0:1], 13
	v_lshl_add_u64 v[6:7], v[0:1], 0, s[0:1]
	s_or_b32 s0, s4, 50
	s_ashr_i32 s1, s0, 31
	s_lshl_b64 s[0:1], s[0:1], 13
	v_lshl_add_u64 v[8:9], v[0:1], 0, s[0:1]
	s_or_b32 s0, s4, 51
	s_ashr_i32 s1, s0, 31
	s_lshl_b64 s[0:1], s[0:1], 13
	v_lshl_add_u64 v[10:11], v[0:1], 0, s[0:1]
	s_or_b32 s0, s4, 52
	s_ashr_i32 s1, s0, 31
	s_lshl_b64 s[0:1], s[0:1], 13
	v_lshl_add_u64 v[12:13], v[0:1], 0, s[0:1]
	s_or_b32 s0, s4, 53
	s_ashr_i32 s1, s0, 31
	s_lshl_b64 s[0:1], s[0:1], 13
	v_lshl_add_u64 v[14:15], v[0:1], 0, s[0:1]
	s_or_b32 s0, s4, 54
	s_ashr_i32 s1, s0, 31
	s_lshl_b64 s[0:1], s[0:1], 13
	v_lshl_add_u64 v[76:77], v[0:1], 0, s[0:1]
	s_or_b32 s0, s4, 55
	s_ashr_i32 s1, s0, 31
	s_lshl_b64 s[0:1], s[0:1], 13
	v_lshl_add_u64 v[78:79], v[0:1], 0, s[0:1]
	s_or_b32 s0, s4, 56
	s_ashr_i32 s1, s0, 31
	s_lshl_b64 s[0:1], s[0:1], 13
	global_load_dword v29, v[2:3], off
	global_load_dword v31, v[6:7], off
	global_load_dword v30, v[8:9], off
	global_load_dword v28, v[10:11], off
	s_nop 0
	global_load_dword v10, v[12:13], off
	s_nop 0
	global_load_dword v12, v[14:15], off
	global_load_dword v11, v[76:77], off
	global_load_dword v9, v[78:79], off
	v_lshl_add_u64 v[2:3], v[0:1], 0, s[0:1]
	s_or_b32 s0, s4, 57
	s_ashr_i32 s1, s0, 31
	s_lshl_b64 s[0:1], s[0:1], 13
	v_lshl_add_u64 v[6:7], v[0:1], 0, s[0:1]
	s_or_b32 s0, s4, 58
	s_ashr_i32 s1, s0, 31
	s_lshl_b64 s[0:1], s[0:1], 13
	v_lshl_add_u64 v[76:77], v[0:1], 0, s[0:1]
	s_or_b32 s0, s4, 59
	s_ashr_i32 s1, s0, 31
	s_lshl_b64 s[0:1], s[0:1], 13
	v_lshl_add_u64 v[78:79], v[0:1], 0, s[0:1]
	s_or_b32 s0, s4, 60
	s_ashr_i32 s1, s0, 31
	s_lshl_b64 s[0:1], s[0:1], 13
	v_lshl_add_u64 v[80:81], v[0:1], 0, s[0:1]
	s_or_b32 s0, s4, 61
	s_ashr_i32 s1, s0, 31
	s_lshl_b64 s[0:1], s[0:1], 13
	v_lshl_add_u64 v[82:83], v[0:1], 0, s[0:1]
	s_or_b32 s0, s4, 62
	s_ashr_i32 s1, s0, 31
	s_lshl_b64 s[0:1], s[0:1], 13
	v_lshl_add_u64 v[84:85], v[0:1], 0, s[0:1]
	s_or_b32 s0, s4, 63
	s_ashr_i32 s1, s0, 31
	s_lshl_b64 s[0:1], s[0:1], 13
	v_lshl_add_u64 v[0:1], v[0:1], 0, s[0:1]
	global_load_dword v14, v[2:3], off
	global_load_dword v20, v[6:7], off
	global_load_dword v15, v[76:77], off
	global_load_dword v13, v[78:79], off
	s_nop 0
	global_load_dword v6, v[80:81], off
	global_load_dword v8, v[82:83], off
	global_load_dword v7, v[84:85], off
	global_load_dword v5, v[0:1], off
	v_readlane_b32 s0, v254, 61
	v_readlane_b32 s1, v254, 62
	s_andn2_b64 vcc, exec, s[0:1]
	v_lshl_add_u32 v22, v4, 2, s29
	v_cndmask_b32_e64 v0, 0, 1, s[0:1]
	v_cmp_ne_u32_e64 s[2:3], 1, v0
	s_cbranch_vccnz .LBB0_480
	s_waitcnt vmcnt(61)
	v_mul_f32_e32 v76, v73, v180
	v_mul_f32_e32 v1, v75, v181
	v_mul_f32_e32 v0, v74, v182
	v_mov_b32_e32 v2, v182
	v_mov_b32_e32 v3, v183
	ds_write2_b32 v22, v76, v1 offset1:65
	s_cbranch_execnz .LBB0_436

; template <bool F8> __device__ __forceinline__ void transpose_item(const float* W, int K, int N, int ld, void* WTv, const float* kscale, float wscale, LAS float* scr, int item, int lane_) {
;     ...
;     for (int kk = 0; kk < 64; ++kk) v[kk] = W[(size_t)(k0 + kk) * ld + n0 + lane];
; #pragma unroll
;     for (int kk = 0; kk < 64; ++kk) { const float sc = (kscale ? kscale[k0 + kk] : 1.f) * wscale; scr[kk * 65 + lane] = v[kk] * sc; }
.LBB0_436:
	s_waitcnt vmcnt(60)
	v_mul_f32_e32 v1, v72, v3
	s_and_b64 vcc, exec, s[2:3]
	v_add_u32_e32 v72, 0x400, v22
	ds_write2_b32 v22, v0, v1 offset0:130 offset1:195
	s_cbranch_vccnz .LBB0_481
	s_waitcnt vmcnt(57)
	v_mul_f32_e32 v73, v65, v184
	v_mul_f32_e32 v1, v67, v185
	v_mul_f32_e32 v0, v66, v186
	v_mov_b32_e32 v2, v186
	v_mov_b32_e32 v3, v187
	ds_write2_b32 v72, v73, v1 offset0:4 offset1:69
	s_cbranch_execnz .LBB0_439

; template <bool F8> __device__ __forceinline__ void transpose_item(const float* W, int K, int N, int ld, void* WTv, const float* kscale, float wscale, LAS float* scr, int item, int lane_) {
;     ...
;     for (int kk = 0; kk < 64; ++kk) v[kk] = W[(size_t)(k0 + kk) * ld + n0 + lane];
; #pragma unroll
;     for (int kk = 0; kk < 64; ++kk) { const float sc = (kscale ? kscale[k0 + kk] : 1.f) * wscale; scr[kk * 65 + lane] = v[kk] * sc; }
.LBB0_439:
	s_waitcnt vmcnt(56)
	v_mul_f32_e32 v1, v64, v3
	s_and_b64 vcc, exec, s[2:3]
	v_add_u32_e32 v64, 0x800, v22
	ds_write2_b32 v72, v0, v1 offset0:134 offset1:199
	s_cbranch_vccnz .LBB0_482
	s_waitcnt vmcnt(53)
	v_mul_f32_e32 v65, v69, v188
	v_mul_f32_e32 v1, v71, v189
	v_mul_f32_e32 v0, v70, v190
	v_mov_b32_e32 v2, v190
	v_mov_b32_e32 v3, v191
	ds_write2_b32 v64, v65, v1 offset0:8 offset1:73
	s_cbranch_execnz .LBB0_442

; template <bool F8> __device__ __forceinline__ void transpose_item(const float* W, int K, int N, int ld, void* WTv, const float* kscale, float wscale, LAS float* scr, int item, int lane_) {
;     ...
;     for (int kk = 0; kk < 64; ++kk) v[kk] = W[(size_t)(k0 + kk) * ld + n0 + lane];
; #pragma unroll
;     for (int kk = 0; kk < 64; ++kk) { const float sc = (kscale ? kscale[k0 + kk] : 1.f) * wscale; scr[kk * 65 + lane] = v[kk] * sc; }
.LBB0_442:
	s_waitcnt vmcnt(52)
	v_mul_f32_e32 v1, v68, v3
	ds_write2_b32 v64, v0, v1 offset0:138 offset1:203
	s_and_b64 vcc, exec, s[2:3]
	v_add_u32_e32 v64, 0xc00, v22
	s_cbranch_vccnz .LBB0_483
	s_waitcnt vmcnt(49)
	v_mul_f32_e32 v65, v57, v192
	v_mul_f32_e32 v1, v59, v193
	v_mul_f32_e32 v0, v58, v194
	v_mov_b32_e32 v2, v194
	v_mov_b32_e32 v3, v195
	ds_write2_b32 v64, v65, v1 offset0:12 offset1:77
	s_cbranch_execnz .LBB0_445

; template <bool F8> __device__ __forceinline__ void transpose_item(const float* W, int K, int N, int ld, void* WTv, const float* kscale, float wscale, LAS float* scr, int item, int lane_) {
;     ...
;     for (int kk = 0; kk < 64; ++kk) v[kk] = W[(size_t)(k0 + kk) * ld + n0 + lane];
; #pragma unroll
;     for (int kk = 0; kk < 64; ++kk) { const float sc = (kscale ? kscale[k0 + kk] : 1.f) * wscale; scr[kk * 65 + lane] = v[kk] * sc; }
.LBB0_445:
	s_waitcnt vmcnt(48)
	v_mul_f32_e32 v1, v56, v3
	s_and_b64 vcc, exec, s[2:3]
	v_add_u32_e32 v56, 0x1000, v22
	ds_write2_b32 v64, v0, v1 offset0:142 offset1:207
	s_cbranch_vccnz .LBB0_484
	s_waitcnt vmcnt(45)
	v_mul_f32_e32 v57, v61, v196
	v_mul_f32_e32 v1, v63, v197
	v_mul_f32_e32 v0, v62, v198
	v_mov_b32_e32 v2, v198
	v_mov_b32_e32 v3, v199
	ds_write2_b32 v56, v57, v1 offset0:16 offset1:81
	s_cbranch_execnz .LBB0_448

; template <bool F8> __device__ __forceinline__ void transpose_item(const float* W, int K, int N, int ld, void* WTv, const float* kscale, float wscale, LAS float* scr, int item, int lane_) {
;     ...
;     for (int kk = 0; kk < 64; ++kk) v[kk] = W[(size_t)(k0 + kk) * ld + n0 + lane];
; #pragma unroll
;     for (int kk = 0; kk < 64; ++kk) { const float sc = (kscale ? kscale[k0 + kk] : 1.f) * wscale; scr[kk * 65 + lane] = v[kk] * sc; }
.LBB0_448:
	s_waitcnt vmcnt(44)
	v_mul_f32_e32 v1, v60, v3
	ds_write2_b32 v56, v0, v1 offset0:146 offset1:211
	s_and_b64 vcc, exec, s[2:3]
	v_add_u32_e32 v56, 0x1400, v22
	s_cbranch_vccnz .LBB0_485
	s_waitcnt vmcnt(41)
	v_mul_f32_e32 v57, v49, v200
	v_mul_f32_e32 v1, v51, v201
	v_mul_f32_e32 v0, v50, v202
	v_mov_b32_e32 v2, v202
	v_mov_b32_e32 v3, v203
	ds_write2_b32 v56, v57, v1 offset0:20 offset1:85
	s_cbranch_execnz .LBB0_451

; template <bool F8> __device__ __forceinline__ void transpose_item(const float* W, int K, int N, int ld, void* WTv, const float* kscale, float wscale, LAS float* scr, int item, int lane_) {
;     ...
;     for (int kk = 0; kk < 64; ++kk) v[kk] = W[(size_t)(k0 + kk) * ld + n0 + lane];
; #pragma unroll
;     for (int kk = 0; kk < 64; ++kk) { const float sc = (kscale ? kscale[k0 + kk] : 1.f) * wscale; scr[kk * 65 + lane] = v[kk] * sc; }
.LBB0_451:
	s_waitcnt vmcnt(40)
	v_mul_f32_e32 v1, v48, v3
	s_and_b64 vcc, exec, s[2:3]
	v_add_u32_e32 v48, 0x1800, v22
	ds_write2_b32 v56, v0, v1 offset0:150 offset1:215
	s_cbranch_vccnz .LBB0_486
	s_waitcnt vmcnt(37)
	v_mul_f32_e32 v49, v53, v204
	v_mul_f32_e32 v1, v55, v205
	v_mul_f32_e32 v0, v54, v206
	v_mov_b32_e32 v2, v206
	v_mov_b32_e32 v3, v207
	ds_write2_b32 v48, v49, v1 offset0:24 offset1:89
	s_cbranch_execnz .LBB0_454

; template <bool F8> __device__ __forceinline__ void transpose_item(const float* W, int K, int N, int ld, void* WTv, const float* kscale, float wscale, LAS float* scr, int item, int lane_) {
;     ...
;     for (int kk = 0; kk < 64; ++kk) v[kk] = W[(size_t)(k0 + kk) * ld + n0 + lane];
; #pragma unroll
;     for (int kk = 0; kk < 64; ++kk) { const float sc = (kscale ? kscale[k0 + kk] : 1.f) * wscale; scr[kk * 65 + lane] = v[kk] * sc; }
.LBB0_454:
	s_waitcnt vmcnt(36)
	v_mul_f32_e32 v1, v52, v3
	ds_write2_b32 v48, v0, v1 offset0:154 offset1:219
	s_and_b64 vcc, exec, s[2:3]
	v_add_u32_e32 v48, 0x1c00, v22
	s_cbranch_vccnz .LBB0_487
	s_waitcnt vmcnt(33)
	v_mul_f32_e32 v49, v41, v208
	v_mul_f32_e32 v1, v43, v209
	v_mul_f32_e32 v0, v42, v210
	v_mov_b32_e32 v2, v210
	v_mov_b32_e32 v3, v211
	ds_write2_b32 v48, v49, v1 offset0:28 offset1:93
	s_cbranch_execnz .LBB0_457

; template <bool F8> __device__ __forceinline__ void transpose_item(const float* W, int K, int N, int ld, void* WTv, const float* kscale, float wscale, LAS float* scr, int item, int lane_) {
;     ...
;     for (int kk = 0; kk < 64; ++kk) v[kk] = W[(size_t)(k0 + kk) * ld + n0 + lane];
; #pragma unroll
;     for (int kk = 0; kk < 64; ++kk) { const float sc = (kscale ? kscale[k0 + kk] : 1.f) * wscale; scr[kk * 65 + lane] = v[kk] * sc; }
.LBB0_457:
	s_waitcnt vmcnt(32)
	v_mul_f32_e32 v1, v40, v3
	s_and_b64 vcc, exec, s[2:3]
	v_add_u32_e32 v40, 0x2000, v22
	ds_write2_b32 v48, v0, v1 offset0:158 offset1:223
	s_cbranch_vccnz .LBB0_488
	s_waitcnt vmcnt(29)
	v_mul_f32_e32 v41, v45, v212
	v_mul_f32_e32 v1, v47, v213
	v_mul_f32_e32 v0, v46, v214
	v_mov_b32_e32 v2, v214
	v_mov_b32_e32 v3, v215
	ds_write2_b32 v40, v41, v1 offset0:32 offset1:97
	s_cbranch_execnz .LBB0_460

; template <bool F8> __device__ __forceinline__ void transpose_item(const float* W, int K, int N, int ld, void* WTv, const float* kscale, float wscale, LAS float* scr, int item, int lane_) {
;     ...
;     for (int kk = 0; kk < 64; ++kk) v[kk] = W[(size_t)(k0 + kk) * ld + n0 + lane];
; #pragma unroll
;     for (int kk = 0; kk < 64; ++kk) { const float sc = (kscale ? kscale[k0 + kk] : 1.f) * wscale; scr[kk * 65 + lane] = v[kk] * sc; }
.LBB0_460:
	s_waitcnt vmcnt(28)
	v_mul_f32_e32 v1, v44, v3
	ds_write2_b32 v40, v0, v1 offset0:162 offset1:227
	s_and_b64 vcc, exec, s[2:3]
	v_add_u32_e32 v40, 0x2400, v22
	s_cbranch_vccnz .LBB0_489
	s_waitcnt vmcnt(25)
	v_mul_f32_e32 v41, v33, v216
	v_mul_f32_e32 v1, v35, v217
	v_mul_f32_e32 v0, v34, v218
	v_mov_b32_e32 v2, v218
	v_mov_b32_e32 v3, v219
	ds_write2_b32 v40, v41, v1 offset0:36 offset1:101
	s_cbranch_execnz .LBB0_463

; template <bool F8> __device__ __forceinline__ void transpose_item(const float* W, int K, int N, int ld, void* WTv, const float* kscale, float wscale, LAS float* scr, int item, int lane_) {
;     ...
;     for (int kk = 0; kk < 64; ++kk) v[kk] = W[(size_t)(k0 + kk) * ld + n0 + lane];
; #pragma unroll
;     for (int kk = 0; kk < 64; ++kk) { const float sc = (kscale ? kscale[k0 + kk] : 1.f) * wscale; scr[kk * 65 + lane] = v[kk] * sc; }
.LBB0_463:
	s_waitcnt vmcnt(24)
	v_mul_f32_e32 v1, v32, v3
	s_and_b64 vcc, exec, s[2:3]
	v_add_u32_e32 v32, 0x2800, v22
	ds_write2_b32 v40, v0, v1 offset0:166 offset1:231
	s_cbranch_vccnz .LBB0_490
	s_waitcnt vmcnt(21)
	v_mul_f32_e32 v33, v37, v220
	v_mul_f32_e32 v1, v39, v221
	v_mul_f32_e32 v0, v38, v222
	v_mov_b32_e32 v2, v222
	v_mov_b32_e32 v3, v223
	ds_write2_b32 v32, v33, v1 offset0:40 offset1:105
	s_cbranch_execnz .LBB0_466

; template <bool F8> __device__ __forceinline__ void transpose_item(const float* W, int K, int N, int ld, void* WTv, const float* kscale, float wscale, LAS float* scr, int item, int lane_) {
;     ...
;     for (int kk = 0; kk < 64; ++kk) v[kk] = W[(size_t)(k0 + kk) * ld + n0 + lane];
; #pragma unroll
;     for (int kk = 0; kk < 64; ++kk) { const float sc = (kscale ? kscale[k0 + kk] : 1.f) * wscale; scr[kk * 65 + lane] = v[kk] * sc; }
.LBB0_466:
	s_waitcnt vmcnt(20)
	v_mul_f32_e32 v1, v36, v3
	ds_write2_b32 v32, v0, v1 offset0:170 offset1:235
	s_and_b64 vcc, exec, s[2:3]
	v_add_u32_e32 v32, 0x2c00, v22
	s_cbranch_vccnz .LBB0_491
	s_waitcnt vmcnt(17)
	v_mul_f32_e32 v33, v25, v224
	v_mul_f32_e32 v1, v27, v225
	v_mul_f32_e32 v0, v26, v226
	v_mov_b32_e32 v2, v226
	v_mov_b32_e32 v3, v227
	ds_write2_b32 v32, v33, v1 offset0:44 offset1:109
	s_cbranch_execnz .LBB0_469

; template <bool F8> __device__ __forceinline__ void transpose_item(const float* W, int K, int N, int ld, void* WTv, const float* kscale, float wscale, LAS float* scr, int item, int lane_) {
;     ...
;     for (int kk = 0; kk < 64; ++kk) v[kk] = W[(size_t)(k0 + kk) * ld + n0 + lane];
; #pragma unroll
;     for (int kk = 0; kk < 64; ++kk) { const float sc = (kscale ? kscale[k0 + kk] : 1.f) * wscale; scr[kk * 65 + lane] = v[kk] * sc; }
.LBB0_469:
	s_waitcnt vmcnt(16)
	v_mul_f32_e32 v1, v24, v3
	s_and_b64 vcc, exec, s[2:3]
	v_add_u32_e32 v24, 0x3000, v22
	ds_write2_b32 v32, v0, v1 offset0:174 offset1:239
	s_cbranch_vccnz .LBB0_492
	s_waitcnt vmcnt(13)
	v_mul_f32_e32 v25, v29, v228
	v_mul_f32_e32 v1, v31, v229
	v_mul_f32_e32 v0, v30, v230
	v_mov_b32_e32 v2, v230
	v_mov_b32_e32 v3, v231
	ds_write2_b32 v24, v25, v1 offset0:48 offset1:113
	s_cbranch_execnz .LBB0_472

; template <bool F8> __device__ __forceinline__ void transpose_item(const float* W, int K, int N, int ld, void* WTv, const float* kscale, float wscale, LAS float* scr, int item, int lane_) {
;     ...
;     for (int kk = 0; kk < 64; ++kk) v[kk] = W[(size_t)(k0 + kk) * ld + n0 + lane];
; #pragma unroll
;     for (int kk = 0; kk < 64; ++kk) { const float sc = (kscale ? kscale[k0 + kk] : 1.f) * wscale; scr[kk * 65 + lane] = v[kk] * sc; }
.LBB0_472:
	s_waitcnt vmcnt(12)
	v_mul_f32_e32 v1, v28, v3
	ds_write2_b32 v24, v0, v1 offset0:178 offset1:243
	s_and_b64 vcc, exec, s[2:3]
	v_add_u32_e32 v24, 0x3400, v22
	s_cbranch_vccnz .LBB0_493
	s_waitcnt vmcnt(9)
	v_mul_f32_e32 v25, v10, v232
	v_mul_f32_e32 v1, v12, v233
	v_mul_f32_e32 v0, v11, v234
	v_mov_b32_e32 v2, v234
	v_mov_b32_e32 v3, v235
	ds_write2_b32 v24, v25, v1 offset0:52 offset1:117
	s_cbranch_execnz .LBB0_475

; template <bool F8> __device__ __forceinline__ void transpose_item(const float* W, int K, int N, int ld, void* WTv, const float* kscale, float wscale, LAS float* scr, int item, int lane_) {
;     ...
;     for (int kk = 0; kk < 64; ++kk) v[kk] = W[(size_t)(k0 + kk) * ld + n0 + lane];
; #pragma unroll
;     for (int kk = 0; kk < 64; ++kk) { const float sc = (kscale ? kscale[k0 + kk] : 1.f) * wscale; scr[kk * 65 + lane] = v[kk] * sc; }
.LBB0_475:
	s_waitcnt vmcnt(8)
	v_mul_f32_e32 v1, v9, v3
	s_and_b64 vcc, exec, s[2:3]
	v_add_u32_e32 v9, 0x3800, v22
	ds_write2_b32 v24, v0, v1 offset0:182 offset1:247
	s_cbranch_vccnz .LBB0_494
	s_waitcnt vmcnt(5)
	v_mul_f32_e32 v10, v14, v236
	v_mul_f32_e32 v1, v20, v237
	v_mul_f32_e32 v0, v15, v238
	v_mov_b32_e32 v2, v238
	v_mov_b32_e32 v3, v239
	ds_write2_b32 v9, v10, v1 offset0:56 offset1:121
	s_cbranch_execnz .LBB0_478

; template <bool F8> __device__ __forceinline__ void transpose_item(const float* W, int K, int N, int ld, void* WTv, const float* kscale, float wscale, LAS float* scr, int item, int lane_) {
;     ...
;     for (int kk = 0; kk < 64; ++kk) v[kk] = W[(size_t)(k0 + kk) * ld + n0 + lane];
; #pragma unroll
;     for (int kk = 0; kk < 64; ++kk) { const float sc = (kscale ? kscale[k0 + kk] : 1.f) * wscale; scr[kk * 65 + lane] = v[kk] * sc; }
.LBB0_478:
	s_waitcnt vmcnt(4)
	v_mul_f32_e32 v1, v13, v3
	ds_write2_b32 v9, v0, v1 offset0:186 offset1:251
	s_and_b64 vcc, exec, s[2:3]
	v_add_u32_e32 v9, 0x3c00, v22
	s_cbranch_vccnz .LBB0_495
	s_waitcnt vmcnt(1)
	v_mul_f32_e32 v10, v6, v240
	v_mul_f32_e32 v1, v8, v241
	v_mul_f32_e32 v0, v7, v242
	v_mov_b32_e32 v2, v242
	v_mov_b32_e32 v3, v243
	ds_write2_b32 v9, v10, v1 offset0:60 offset1:125
	s_cbranch_execnz .LBB0_432
	s_branch .LBB0_496
